# adds: P1/P9 row output stage loads of norm/shift/scale vectors pipelined 2 groups ahead; attention loop m0 save/restore and zero-adds removed
# baseline (speedup 1.0000x reference)
; __device__ __forceinline__ float wave_sum(float v) {
; #pragma unroll
;     for (int o = 1; o < 64; o <<= 1) v += __shfl_xor(v, o);
;     return v;
.LBB0_65:
	v_mov_b32_e32 v98, v89
	v_mov_b32_e32 v99, v93
	v_mov_b32_e32 v96, v88
	v_mov_b32_e32 v97, v92
	v_pk_mul_f32 v[98:99], v[98:99], v[98:99]
	v_mov_b32_e32 v100, v91
	v_mov_b32_e32 v101, v95
	v_pk_fma_f32 v[96:97], v[96:97], v[96:97], v[98:99]
	v_mov_b32_e32 v98, v90
	v_mov_b32_e32 v99, v94
	v_pk_mul_f32 v[100:101], v[100:101], v[100:101]
	s_add_i32 s7, s64, 0xffff8000
	v_pk_fma_f32 v[98:99], v[98:99], v[98:99], v[100:101]
	v_pk_mul_f32 v[100:101], v[84:85], v[84:85]
	v_pk_add_f32 v[96:97], v[96:97], v[98:99]
	v_pk_mul_f32 v[98:99], v[86:87], v[86:87]
	v_pk_add_f32 v[96:97], v[96:97], v[96:97] op_sel_hi:[0,1]
	v_pk_mov_b32 v[102:103], v[100:101], v[98:99] op_sel:[1,0]
	v_mov_b32_e32 v101, v99
	v_mul_f32_e32 v96, v80, v80
	v_pk_add_f32 v[98:99], v[102:103], v[100:101]
	v_pk_fma_f32 v[100:101], v[80:81], v[80:81], v[96:97] op_sel_hi:[1,1,0]
	v_mul_f32_e32 v96, v82, v82
	v_pk_add_f32 v[98:99], v[98:99], v[98:99] op_sel_hi:[0,1]
	v_pk_fma_f32 v[102:103], v[82:83], v[82:83], v[96:97] op_sel_hi:[1,1,0]
	v_mul_f32_e32 v100, v76, v76
	v_mul_f32_e32 v102, v77, v77
	v_mul_f32_e32 v98, v78, v78
	v_mul_f32_e32 v96, v79, v79
	v_pk_add_f32 v[100:101], v[100:101], v[102:103]
	v_pk_add_f32 v[96:97], v[98:99], v[96:97]
	s_lshr_b32 s7, s7, 6
	v_pk_add_f32 v[96:97], v[100:101], v[96:97]
	v_pk_mul_f32 v[98:99], v[74:75], v[74:75]
	v_pk_add_f32 v[96:97], v[96:97], v[96:97] op_sel_hi:[0,1]
	v_pk_mul_f32 v[100:101], v[72:73], v[72:73]
	s_ashr_i32 s6, s64, 14
	s_add_i32 s7, s7, 2
	v_pk_mov_b32 v[102:103], v[100:101], v[98:99] op_sel:[1,0]
	v_mov_b32_e32 v101, v99
	v_mul_f32_e32 v96, v68, v68
	s_cmp_lt_i32 s64, 0x8000
	v_pk_add_f32 v[98:99], v[102:103], v[100:101]
	v_pk_fma_f32 v[100:101], v[68:69], v[68:69], v[96:97] op_sel_hi:[1,1,0]
	v_mul_f32_e32 v96, v70, v70
	s_cselect_b32 s8, s6, s7
	v_pk_add_f32 v[98:99], v[98:99], v[98:99] op_sel_hi:[0,1]
	v_pk_fma_f32 v[102:103], v[70:71], v[70:71], v[96:97] op_sel_hi:[1,1,0]
	v_mul_f32_e32 v100, v64, v64
	v_mul_f32_e32 v102, v65, v65
	v_mul_f32_e32 v98, v66, v66
	v_mul_f32_e32 v96, v67, v67
	v_mad_i64_i32 v[112:113], s[6:7], s8, v190, v[142:143]
	v_pk_add_f32 v[108:109], v[100:101], v[102:103]
	v_pk_add_f32 v[110:111], v[98:99], v[96:97]
	global_load_dwordx4 v[96:99], v[130:131], off
	v_mad_i64_i32 v[114:115], s[6:7], s8, v190, v[144:145]
	global_load_dwordx4 v[100:103], v[112:113], off
	global_load_dwordx4 v[104:107], v[114:115], off
	global_load_dwordx4 v[220:223], v[130:131], off offset:1024
	global_load_dwordx4 v[224:227], v[114:115], off offset:1024
	global_load_dwordx4 v[228:231], v[112:113], off offset:1024
	global_load_dwordx4 v[232:235], v[130:131], off offset:2048
	global_load_dwordx4 v[236:239], v[114:115], off offset:2048
	global_load_dwordx4 v[240:243], v[112:113], off offset:2048
	v_pk_add_f32 v[108:109], v[108:109], v[110:111]
	s_nop 0
	v_add_f32_e32 v108, v108, v109
	ds_bpermute_b32 v109, v191, v108
	s_waitcnt lgkmcnt(0)
	v_add_f32_e32 v108, v108, v109
	ds_bpermute_b32 v109, v192, v108
	s_waitcnt lgkmcnt(0)
	v_add_f32_e32 v108, v108, v109
	ds_bpermute_b32 v109, v193, v108
	s_waitcnt lgkmcnt(0)
	v_add_f32_e32 v108, v108, v109
	ds_bpermute_b32 v109, v194, v108
	s_waitcnt lgkmcnt(0)
	v_add_f32_e32 v108, v108, v109
	ds_bpermute_b32 v109, v195, v108
	s_waitcnt lgkmcnt(0)
	v_add_f32_e32 v108, v108, v109
	ds_bpermute_b32 v109, v196, v108
	s_waitcnt lgkmcnt(0)
	v_add_f32_e32 v108, v108, v109
	v_fmamk_f32 v108, v108, 0x3a000000, v180
	v_mul_f32_e32 v109, 0x4f800000, v108
	v_cmp_gt_f32_e32 vcc, s2, v108
	s_nop 1
	v_cndmask_b32_e32 v108, v108, v109, vcc
	v_sqrt_f32_e32 v109, v108
	s_nop 0
	v_add_u32_e32 v110, -1, v109
	v_fma_f32 v111, -v110, v109, v108
	v_cmp_ge_f32_e64 s[6:7], 0, v111
	v_add_u32_e32 v111, 1, v109
	s_nop 0
	v_cndmask_b32_e64 v110, v109, v110, s[6:7]
	v_fma_f32 v109, -v111, v109, v108
	v_cmp_lt_f32_e64 s[6:7], 0, v109
	s_nop 1
	v_cndmask_b32_e64 v109, v110, v111, s[6:7]
	v_mul_f32_e32 v110, 0x37800000, v109
	v_cndmask_b32_e32 v109, v109, v110, vcc
	v_cmp_class_f32_e32 vcc, v108, v181
	s_nop 1
	v_cndmask_b32_e32 v108, v109, v108, vcc
	v_div_scale_f32 v109, s[6:7], v108, v108, 1.0
	v_rcp_f32_e32 v110, v109
	s_nop 0
	v_fma_f32 v111, -v109, v110, 1.0
	v_fmac_f32_e32 v110, v111, v110
	v_div_scale_f32 v111, vcc, 1.0, v108, 1.0
	v_mul_f32_e32 v116, v111, v110
	v_fma_f32 v117, -v109, v116, v111
	v_fmac_f32_e32 v116, v117, v110
	v_fma_f32 v109, -v109, v116, v111
	v_div_fmas_f32 v109, v109, v110, v116
	v_div_fixup_f32 v108, v109, v108, 1.0
	v_pk_mul_f32 v[94:95], v[108:109], v[94:95] op_sel_hi:[0,1]
	v_pk_mul_f32 v[92:93], v[108:109], v[92:93] op_sel_hi:[0,1]
	s_waitcnt vmcnt(8)
	v_pk_mul_f32 v[92:93], v[96:97], v[92:93]
	v_pk_mul_f32 v[94:95], v[98:99], v[94:95]
	s_waitcnt vmcnt(6)
	v_pk_add_f32 v[96:97], v[106:107], 1.0 op_sel_hi:[1,0]
	v_pk_add_f32 v[98:99], v[104:105], 1.0 op_sel_hi:[1,0]
	v_pk_fma_f32 v[94:95], v[96:97], v[94:95], v[102:103]
	v_pk_fma_f32 v[92:93], v[98:99], v[92:93], v[100:101]
	v_lshl_add_u64 v[104:105], s[62:63], 1, v[146:147]
	v_cvt_pk_bf16_f32 v92, v92, v93
	v_cvt_pk_bf16_f32 v93, v94, v95
	global_store_dwordx2 v[104:105], v[92:93], off
	s_nop 1
	v_add_co_u32_e32 v96, vcc, s1, v114
	s_nop 1
	v_addc_co_u32_e32 v97, vcc, 0, v115, vcc
	v_add_co_u32_e32 v92, vcc, s1, v112
	s_nop 1
	v_addc_co_u32_e32 v93, vcc, 0, v113, vcc
	v_pk_mul_f32 v[90:91], v[108:109], v[90:91] op_sel_hi:[0,1]
	v_pk_mul_f32 v[88:89], v[108:109], v[88:89] op_sel_hi:[0,1]
	v_pk_mul_f32 v[86:87], v[108:109], v[86:87] op_sel_hi:[0,1]
	v_pk_mul_f32 v[84:85], v[108:109], v[84:85] op_sel_hi:[0,1]
	v_pk_mul_f32 v[82:83], v[108:109], v[82:83] op_sel_hi:[0,1]
	v_pk_mul_f32 v[80:81], v[108:109], v[80:81] op_sel_hi:[0,1]
	v_pk_mul_f32 v[78:79], v[108:109], v[78:79] op_sel_hi:[0,1]
	v_pk_mul_f32 v[76:77], v[108:109], v[76:77] op_sel_hi:[0,1]
	v_pk_mul_f32 v[74:75], v[108:109], v[74:75] op_sel_hi:[0,1]
	v_pk_mul_f32 v[72:73], v[108:109], v[72:73] op_sel_hi:[0,1]
	v_pk_mul_f32 v[70:71], v[108:109], v[70:71] op_sel_hi:[0,1]
	v_pk_mul_f32 v[68:69], v[108:109], v[68:69] op_sel_hi:[0,1]
	v_pk_mul_f32 v[66:67], v[108:109], v[66:67] op_sel_hi:[0,1]
	v_pk_mul_f32 v[64:65], v[108:109], v[64:65] op_sel_hi:[0,1]
	s_waitcnt vmcnt(6)
	v_pk_mul_f32 v[88:89], v[220:221], v[88:89]
	v_pk_mul_f32 v[90:91], v[222:223], v[90:91]
	s_waitcnt vmcnt(5)
	v_pk_add_f32 v[220:221], v[226:227], 1.0 op_sel_hi:[1,0]
	v_pk_add_f32 v[222:223], v[224:225], 1.0 op_sel_hi:[1,0]
	s_waitcnt vmcnt(4)
	v_pk_fma_f32 v[90:91], v[220:221], v[90:91], v[230:231]
	v_pk_fma_f32 v[88:89], v[222:223], v[88:89], v[228:229]
	s_nop 0
	v_cvt_pk_bf16_f32 v88, v88, v89
	v_cvt_pk_bf16_f32 v89, v90, v91
	global_store_dwordx2 v[104:105], v[88:89], off offset:512
	global_load_dwordx4 v[220:223], v[130:131], off offset:3072
	global_load_dwordx4 v[224:227], v[114:115], off offset:3072
	global_load_dwordx4 v[228:231], v[112:113], off offset:3072
	s_waitcnt vmcnt(7)
	v_pk_mul_f32 v[84:85], v[232:233], v[84:85]
	v_pk_mul_f32 v[86:87], v[234:235], v[86:87]
	s_waitcnt vmcnt(6)
	v_pk_add_f32 v[232:233], v[238:239], 1.0 op_sel_hi:[1,0]
	v_pk_add_f32 v[234:235], v[236:237], 1.0 op_sel_hi:[1,0]
	s_waitcnt vmcnt(5)
	v_pk_fma_f32 v[86:87], v[232:233], v[86:87], v[242:243]
	v_pk_fma_f32 v[84:85], v[234:235], v[84:85], v[240:241]
	v_cvt_pk_bf16_f32 v84, v84, v85
	v_cvt_pk_bf16_f32 v85, v86, v87
	global_store_dwordx2 v[104:105], v[84:85], off offset:1024
	global_load_dwordx4 v[232:235], v[132:133], off
	global_load_dwordx4 v[236:239], v[96:97], off
	global_load_dwordx4 v[240:243], v[92:93], off
	s_waitcnt vmcnt(6)
	v_pk_mul_f32 v[80:81], v[220:221], v[80:81]
	v_pk_mul_f32 v[82:83], v[222:223], v[82:83]
	s_waitcnt vmcnt(5)
	v_pk_add_f32 v[220:221], v[226:227], 1.0 op_sel_hi:[1,0]
	v_pk_add_f32 v[222:223], v[224:225], 1.0 op_sel_hi:[1,0]
	s_waitcnt vmcnt(4)
	v_pk_fma_f32 v[82:83], v[220:221], v[82:83], v[230:231]
	v_pk_fma_f32 v[80:81], v[222:223], v[80:81], v[228:229]
	v_cvt_pk_bf16_f32 v80, v80, v81
	v_cvt_pk_bf16_f32 v81, v82, v83
	global_store_dwordx2 v[104:105], v[80:81], off offset:1536
	global_load_dwordx4 v[220:223], v[134:135], off
	global_load_dwordx4 v[224:227], v[96:97], off offset:1024
	global_load_dwordx4 v[228:231], v[92:93], off offset:1024
	s_waitcnt vmcnt(6)
	v_pk_mul_f32 v[76:77], v[232:233], v[76:77]
	v_pk_mul_f32 v[78:79], v[234:235], v[78:79]
	s_waitcnt vmcnt(5)
	v_pk_add_f32 v[232:233], v[238:239], 1.0 op_sel_hi:[1,0]
	v_pk_add_f32 v[234:235], v[236:237], 1.0 op_sel_hi:[1,0]
	s_waitcnt vmcnt(4)
	v_pk_fma_f32 v[78:79], v[232:233], v[78:79], v[242:243]
	v_pk_fma_f32 v[76:77], v[234:235], v[76:77], v[240:241]
	s_nop 0
	v_cvt_pk_bf16_f32 v76, v76, v77
	v_cvt_pk_bf16_f32 v77, v78, v79
	global_store_dwordx2 v[104:105], v[76:77], off offset:2048
	global_load_dwordx4 v[232:235], v[136:137], off
	global_load_dwordx4 v[236:239], v[96:97], off offset:2048
	global_load_dwordx4 v[240:243], v[92:93], off offset:2048
	s_waitcnt vmcnt(6)
	v_pk_mul_f32 v[72:73], v[72:73], v[220:221]
	v_pk_mul_f32 v[74:75], v[74:75], v[222:223]
	s_waitcnt vmcnt(5)
	v_pk_add_f32 v[220:221], v[226:227], 1.0 op_sel_hi:[1,0]
	v_pk_add_f32 v[222:223], v[224:225], 1.0 op_sel_hi:[1,0]
	s_waitcnt vmcnt(4)
	v_pk_fma_f32 v[74:75], v[74:75], v[220:221], v[230:231]
	v_pk_fma_f32 v[72:73], v[72:73], v[222:223], v[228:229]
	s_nop 0
	v_cvt_pk_bf16_f32 v72, v72, v73
	v_cvt_pk_bf16_f32 v73, v74, v75
	global_store_dwordx2 v[104:105], v[72:73], off offset:2560
	global_load_dwordx4 v[220:223], v[138:139], off
	global_load_dwordx4 v[224:227], v[96:97], off offset:3072
	global_load_dwordx4 v[228:231], v[92:93], off offset:3072
	s_waitcnt vmcnt(6)
	v_pk_mul_f32 v[68:69], v[68:69], v[232:233]
	v_pk_mul_f32 v[70:71], v[70:71], v[234:235]
	s_waitcnt vmcnt(5)
	v_pk_add_f32 v[232:233], v[238:239], 1.0 op_sel_hi:[1,0]
	v_pk_add_f32 v[234:235], v[236:237], 1.0 op_sel_hi:[1,0]
	s_waitcnt vmcnt(4)
	v_pk_fma_f32 v[70:71], v[70:71], v[232:233], v[242:243]
	v_pk_fma_f32 v[68:69], v[68:69], v[234:235], v[240:241]
	s_nop 0
	v_cvt_pk_bf16_f32 v68, v68, v69
	v_cvt_pk_bf16_f32 v69, v70, v71
	global_store_dwordx2 v[104:105], v[68:69], off offset:3072
	s_waitcnt vmcnt(3)
	v_pk_mul_f32 v[64:65], v[64:65], v[220:221]
	v_pk_mul_f32 v[66:67], v[66:67], v[222:223]
	s_waitcnt vmcnt(2)
	v_pk_add_f32 v[220:221], v[226:227], 1.0 op_sel_hi:[1,0]
	v_pk_add_f32 v[222:223], v[224:225], 1.0 op_sel_hi:[1,0]
	s_waitcnt vmcnt(1)
	v_pk_fma_f32 v[66:67], v[66:67], v[220:221], v[230:231]
	v_pk_fma_f32 v[64:65], v[64:65], v[222:223], v[228:229]
	s_nop 0
	v_cvt_pk_bf16_f32 v64, v64, v65
	v_cvt_pk_bf16_f32 v65, v66, v67
	global_store_dwordx2 v[104:105], v[64:65], off offset:3584

.LBB0_87:
	v_pk_mul_f32 v[210:211], v[126:127], v[126:127]
	v_pk_mul_f32 v[212:213], v[122:123], v[122:123]
	v_pk_mul_f32 v[206:207], v[124:125], v[124:125]
	v_pk_mul_f32 v[208:209], v[120:121], v[120:121]
	v_mov_b32_e32 v214, v210
	v_mov_b32_e32 v215, v212
	v_mov_b32_e32 v212, v211
	v_pk_mul_f32 v[202:203], v[116:117], v[116:117]
	v_pk_mul_f32 v[204:205], v[118:119], v[118:119]
	v_pk_add_f32 v[210:211], v[214:215], v[212:213]
	v_mov_b32_e32 v212, v206
	v_mov_b32_e32 v213, v208
	v_mov_b32_e32 v208, v207
	v_pk_add_f32 v[206:207], v[212:213], v[208:209]
	v_pk_mov_b32 v[208:209], v[204:205], v[202:203] op_sel:[1,0]
	v_mov_b32_e32 v205, v203
	v_pk_add_f32 v[202:203], v[208:209], v[204:205]
	v_pk_add_f32 v[206:207], v[210:211], v[206:207]
	v_pk_add_f32 v[202:203], v[202:203], v[202:203] op_sel_hi:[0,1]
	v_mul_f32_e32 v202, v114, v114
	v_pk_fma_f32 v[204:205], v[114:115], v[114:115], v[202:203] op_sel_hi:[1,1,0]
	v_mul_f32_e32 v202, v112, v112
	v_pk_add_f32 v[206:207], v[206:207], v[206:207] op_sel_hi:[0,1]
	v_pk_fma_f32 v[208:209], v[112:113], v[112:113], v[202:203] op_sel_hi:[1,1,0]
	v_mul_f32_e32 v204, v108, v108
	v_mul_f32_e32 v208, v109, v109
	v_mul_f32_e32 v202, v110, v110
	v_mul_f32_e32 v206, v111, v111
	v_pk_mul_f32 v[198:199], v[104:105], v[104:105]
	v_pk_mul_f32 v[200:201], v[106:107], v[106:107]
	v_pk_add_f32 v[204:205], v[204:205], v[208:209]
	v_pk_add_f32 v[202:203], v[202:203], v[206:207]
	s_add_i32 s7, s46, 0xffff8000
	v_pk_add_f32 v[202:203], v[204:205], v[202:203]
	v_pk_mov_b32 v[204:205], v[200:201], v[198:199] op_sel:[1,0]
	v_mov_b32_e32 v201, v199
	v_pk_add_f32 v[198:199], v[204:205], v[200:201]
	s_lshr_b32 s7, s7, 6
	v_pk_add_f32 v[198:199], v[198:199], v[198:199] op_sel_hi:[0,1]
	s_ashr_i32 s6, s46, 14
	s_add_i32 s7, s7, 2
	v_mul_f32_e32 v198, v102, v102
	s_cmp_lt_i32 s46, 0x8000
	v_pk_fma_f32 v[200:201], v[102:103], v[102:103], v[198:199] op_sel_hi:[1,1,0]
	v_mul_f32_e32 v198, v100, v100
	s_cselect_b32 s8, s6, s7
	v_pk_add_f32 v[202:203], v[202:203], v[202:203] op_sel_hi:[0,1]
	v_pk_fma_f32 v[204:205], v[100:101], v[100:101], v[198:199] op_sel_hi:[1,1,0]
	v_mul_f32_e32 v200, v98, v98
	v_mul_f32_e32 v204, v99, v99
	v_mul_f32_e32 v198, v96, v96
	v_mul_f32_e32 v202, v97, v97
	v_mad_i64_i32 v[214:215], s[6:7], s8, v190, v[142:143]
	v_pk_add_f32 v[210:211], v[200:201], v[204:205]
	v_pk_add_f32 v[212:213], v[198:199], v[202:203]
	global_load_dwordx4 v[198:201], v[130:131], off
	v_mad_i64_i32 v[216:217], s[6:7], s8, v190, v[144:145]
	global_load_dwordx4 v[202:205], v[214:215], off
	global_load_dwordx4 v[206:209], v[216:217], off
	global_load_dwordx4 v[220:223], v[130:131], off offset:1024
	global_load_dwordx4 v[224:227], v[216:217], off offset:1024
	global_load_dwordx4 v[228:231], v[214:215], off offset:1024
	global_load_dwordx4 v[232:235], v[130:131], off offset:2048
	global_load_dwordx4 v[236:239], v[216:217], off offset:2048
	global_load_dwordx4 v[240:243], v[214:215], off offset:2048
	v_pk_add_f32 v[210:211], v[210:211], v[212:213]
	s_nop 0
	v_add_f32_e32 v197, v210, v211
	ds_bpermute_b32 v210, v191, v197
	s_waitcnt lgkmcnt(0)
	v_add_f32_e32 v197, v197, v210
	ds_bpermute_b32 v210, v192, v197
	s_waitcnt lgkmcnt(0)
	v_add_f32_e32 v197, v197, v210
	ds_bpermute_b32 v210, v193, v197
	s_waitcnt lgkmcnt(0)
	v_add_f32_e32 v197, v197, v210
	ds_bpermute_b32 v210, v194, v197
	s_waitcnt lgkmcnt(0)
	v_add_f32_e32 v197, v197, v210
	ds_bpermute_b32 v210, v195, v197
	s_waitcnt lgkmcnt(0)
	v_add_f32_e32 v197, v197, v210
	ds_bpermute_b32 v210, v196, v197
	s_waitcnt lgkmcnt(0)
	v_add_f32_e32 v197, v197, v210
	v_fmamk_f32 v197, v197, 0x3a000000, v180
	v_mul_f32_e32 v210, 0x4f800000, v197
	v_cmp_gt_f32_e32 vcc, s2, v197
	s_nop 1
	v_cndmask_b32_e32 v197, v197, v210, vcc
	v_sqrt_f32_e32 v210, v197
	s_nop 0
	v_add_u32_e32 v211, -1, v210
	v_fma_f32 v212, -v211, v210, v197
	v_cmp_ge_f32_e64 s[6:7], 0, v212
	v_add_u32_e32 v212, 1, v210
	s_nop 0
	v_cndmask_b32_e64 v211, v210, v211, s[6:7]
	v_fma_f32 v210, -v212, v210, v197
	v_cmp_lt_f32_e64 s[6:7], 0, v210
	s_nop 1
	v_cndmask_b32_e64 v210, v211, v212, s[6:7]
	v_mul_f32_e32 v211, 0x37800000, v210
	v_cndmask_b32_e32 v210, v210, v211, vcc
	v_cmp_class_f32_e32 vcc, v197, v181
	s_nop 1
	v_cndmask_b32_e32 v197, v210, v197, vcc
	v_div_scale_f32 v210, s[6:7], v197, v197, 1.0
	v_rcp_f32_e32 v211, v210
	s_nop 0
	v_fma_f32 v212, -v210, v211, 1.0
	v_fmac_f32_e32 v211, v212, v211
	v_div_scale_f32 v212, vcc, 1.0, v197, 1.0
	v_mul_f32_e32 v213, v212, v211
	v_fma_f32 v218, -v210, v213, v212
	v_fmac_f32_e32 v213, v218, v211
	v_fma_f32 v210, -v210, v213, v212
	v_div_fmas_f32 v210, v210, v211, v213
	v_div_fixup_f32 v210, v210, v197, 1.0
	v_pk_mul_f32 v[124:125], v[124:125], v[210:211] op_sel_hi:[1,0]
	v_pk_mul_f32 v[126:127], v[126:127], v[210:211] op_sel_hi:[1,0]
	s_waitcnt vmcnt(6)
	v_pk_mul_f32 v[124:125], v[200:201], v[124:125]
	v_pk_mul_f32 v[126:127], v[198:199], v[126:127]
	v_pk_add_f32 v[198:199], v[208:209], 1.0 op_sel_hi:[1,0]
	v_pk_add_f32 v[200:201], v[206:207], 1.0 op_sel_hi:[1,0]
	v_pk_fma_f32 v[124:125], v[198:199], v[124:125], v[204:205]
	v_pk_fma_f32 v[126:127], v[200:201], v[126:127], v[202:203]
	v_lshl_add_u64 v[206:207], s[76:77], 1, v[146:147]
	v_cvt_pk_bf16_f32 v126, v126, v127
	v_cvt_pk_bf16_f32 v127, v124, v125
	global_store_dwordx2 v[206:207], v[126:127], off
	s_nop 1
	v_add_co_u32_e32 v198, vcc, s1, v216
	s_nop 1
	v_addc_co_u32_e32 v199, vcc, 0, v217, vcc
	v_add_co_u32_e32 v124, vcc, s1, v214
	s_nop 1
	v_addc_co_u32_e32 v125, vcc, 0, v215, vcc
	v_pk_mul_f32 v[120:121], v[120:121], v[210:211] op_sel_hi:[1,0]
	v_pk_mul_f32 v[122:123], v[122:123], v[210:211] op_sel_hi:[1,0]
	v_pk_mul_f32 v[116:117], v[116:117], v[210:211] op_sel_hi:[1,0]
	v_pk_mul_f32 v[118:119], v[118:119], v[210:211] op_sel_hi:[1,0]
	v_pk_mul_f32 v[112:113], v[112:113], v[210:211] op_sel_hi:[1,0]
	v_pk_mul_f32 v[114:115], v[114:115], v[210:211] op_sel_hi:[1,0]
	v_pk_mul_f32 v[110:111], v[110:111], v[210:211] op_sel_hi:[1,0]
	v_pk_mul_f32 v[108:109], v[108:109], v[210:211] op_sel_hi:[1,0]
	v_pk_mul_f32 v[104:105], v[104:105], v[210:211] op_sel_hi:[1,0]
	v_pk_mul_f32 v[106:107], v[106:107], v[210:211] op_sel_hi:[1,0]
	v_pk_mul_f32 v[100:101], v[100:101], v[210:211] op_sel_hi:[1,0]
	v_pk_mul_f32 v[102:103], v[102:103], v[210:211] op_sel_hi:[1,0]
	v_pk_mul_f32 v[96:97], v[96:97], v[210:211] op_sel_hi:[1,0]
	v_pk_mul_f32 v[98:99], v[98:99], v[210:211] op_sel_hi:[1,0]
	s_waitcnt vmcnt(6)
	v_pk_mul_f32 v[122:123], v[220:221], v[122:123]
	v_pk_mul_f32 v[120:121], v[222:223], v[120:121]
	s_waitcnt vmcnt(5)
	v_pk_add_f32 v[220:221], v[226:227], 1.0 op_sel_hi:[1,0]
	v_pk_add_f32 v[222:223], v[224:225], 1.0 op_sel_hi:[1,0]
	s_waitcnt vmcnt(4)
	v_pk_fma_f32 v[120:121], v[220:221], v[120:121], v[230:231]
	v_pk_fma_f32 v[122:123], v[222:223], v[122:123], v[228:229]
	s_nop 0
	v_cvt_pk_bf16_f32 v122, v122, v123
	v_cvt_pk_bf16_f32 v123, v120, v121
	global_store_dwordx2 v[206:207], v[122:123], off offset:512
	global_load_dwordx4 v[220:223], v[130:131], off offset:3072
	global_load_dwordx4 v[224:227], v[216:217], off offset:3072
	global_load_dwordx4 v[228:231], v[214:215], off offset:3072
	s_waitcnt vmcnt(7)
	v_pk_mul_f32 v[118:119], v[232:233], v[118:119]
	v_pk_mul_f32 v[116:117], v[234:235], v[116:117]
	s_waitcnt vmcnt(6)
	v_pk_add_f32 v[232:233], v[238:239], 1.0 op_sel_hi:[1,0]
	v_pk_add_f32 v[234:235], v[236:237], 1.0 op_sel_hi:[1,0]
	s_waitcnt vmcnt(5)
	v_pk_fma_f32 v[116:117], v[232:233], v[116:117], v[242:243]
	v_pk_fma_f32 v[118:119], v[234:235], v[118:119], v[240:241]
	v_cvt_pk_bf16_f32 v118, v118, v119
	v_cvt_pk_bf16_f32 v119, v116, v117
	global_store_dwordx2 v[206:207], v[118:119], off offset:1024
	global_load_dwordx4 v[232:235], v[132:133], off
	global_load_dwordx4 v[236:239], v[198:199], off
	global_load_dwordx4 v[240:243], v[124:125], off
	s_waitcnt vmcnt(6)
	v_pk_mul_f32 v[114:115], v[220:221], v[114:115]
	v_pk_mul_f32 v[112:113], v[222:223], v[112:113]
	s_waitcnt vmcnt(5)
	v_pk_add_f32 v[220:221], v[226:227], 1.0 op_sel_hi:[1,0]
	v_pk_add_f32 v[222:223], v[224:225], 1.0 op_sel_hi:[1,0]
	s_waitcnt vmcnt(4)
	v_pk_fma_f32 v[112:113], v[220:221], v[112:113], v[230:231]
	v_pk_fma_f32 v[114:115], v[222:223], v[114:115], v[228:229]
	v_cvt_pk_bf16_f32 v114, v114, v115
	v_cvt_pk_bf16_f32 v115, v112, v113
	global_store_dwordx2 v[206:207], v[114:115], off offset:1536
	global_load_dwordx4 v[220:223], v[134:135], off
	global_load_dwordx4 v[224:227], v[198:199], off offset:1024
	global_load_dwordx4 v[228:231], v[124:125], off offset:1024
	s_andn2_b64 vcc, exec, s[74:75]
	s_waitcnt vmcnt(6)
	v_pk_mul_f32 v[108:109], v[232:233], v[108:109]
	v_pk_mul_f32 v[110:111], v[234:235], v[110:111]
	s_waitcnt vmcnt(5)
	v_pk_add_f32 v[232:233], v[238:239], 1.0 op_sel_hi:[1,0]
	v_pk_add_f32 v[234:235], v[236:237], 1.0 op_sel_hi:[1,0]
	s_waitcnt vmcnt(4)
	v_pk_fma_f32 v[110:111], v[110:111], v[232:233], v[242:243]
	v_pk_fma_f32 v[108:109], v[108:109], v[234:235], v[240:241]
	s_nop 0
	v_cvt_pk_bf16_f32 v108, v108, v109
	v_cvt_pk_bf16_f32 v109, v110, v111
	global_store_dwordx2 v[206:207], v[108:109], off offset:2048
	global_load_dwordx4 v[232:235], v[136:137], off
	global_load_dwordx4 v[236:239], v[198:199], off offset:2048
	global_load_dwordx4 v[240:243], v[124:125], off offset:2048
	s_waitcnt vmcnt(6)
	v_pk_mul_f32 v[106:107], v[106:107], v[220:221]
	v_pk_mul_f32 v[104:105], v[104:105], v[222:223]
	s_waitcnt vmcnt(5)
	v_pk_add_f32 v[220:221], v[226:227], 1.0 op_sel_hi:[1,0]
	v_pk_add_f32 v[222:223], v[224:225], 1.0 op_sel_hi:[1,0]
	s_waitcnt vmcnt(4)
	v_pk_fma_f32 v[104:105], v[104:105], v[220:221], v[230:231]
	v_pk_fma_f32 v[106:107], v[106:107], v[222:223], v[228:229]
	s_nop 0
	v_cvt_pk_bf16_f32 v106, v106, v107
	v_cvt_pk_bf16_f32 v107, v104, v105
	global_store_dwordx2 v[206:207], v[106:107], off offset:2560
	global_load_dwordx4 v[220:223], v[138:139], off
	global_load_dwordx4 v[224:227], v[198:199], off offset:3072
	global_load_dwordx4 v[228:231], v[124:125], off offset:3072
	s_waitcnt vmcnt(6)
	v_pk_mul_f32 v[102:103], v[102:103], v[232:233]
	v_pk_mul_f32 v[100:101], v[100:101], v[234:235]
	s_waitcnt vmcnt(5)
	v_pk_add_f32 v[232:233], v[238:239], 1.0 op_sel_hi:[1,0]
	v_pk_add_f32 v[234:235], v[236:237], 1.0 op_sel_hi:[1,0]
	s_waitcnt vmcnt(4)
	v_pk_fma_f32 v[100:101], v[100:101], v[232:233], v[242:243]
	v_pk_fma_f32 v[102:103], v[102:103], v[234:235], v[240:241]
	s_nop 0
	v_cvt_pk_bf16_f32 v102, v102, v103
	v_cvt_pk_bf16_f32 v103, v100, v101
	global_store_dwordx2 v[206:207], v[102:103], off offset:3072
	s_waitcnt vmcnt(3)
	v_pk_mul_f32 v[98:99], v[98:99], v[220:221]
	v_pk_mul_f32 v[96:97], v[96:97], v[222:223]
	s_waitcnt vmcnt(2)
	v_pk_add_f32 v[220:221], v[226:227], 1.0 op_sel_hi:[1,0]
	v_pk_add_f32 v[222:223], v[224:225], 1.0 op_sel_hi:[1,0]
	s_waitcnt vmcnt(1)
	v_pk_fma_f32 v[96:97], v[96:97], v[220:221], v[230:231]
	v_pk_fma_f32 v[98:99], v[98:99], v[222:223], v[228:229]
	s_nop 0
	v_cvt_pk_bf16_f32 v98, v98, v99
	v_cvt_pk_bf16_f32 v99, v96, v97
	global_store_dwordx2 v[206:207], v[98:99], off offset:3584
	s_cbranch_vccnz .LBB0_66
	s_cmp_lg_u64 s[66:67], 0
	s_cbranch_scc1 .LBB0_65
	v_lshlrev_b32_e32 v92, 16, v178
	v_and_b32_e32 v93, 0xffff0000, v178
	v_lshlrev_b32_e32 v94, 16, v179
	v_and_b32_e32 v95, 0xffff0000, v179
	v_lshlrev_b32_e32 v88, 16, v176
	v_and_b32_e32 v89, 0xffff0000, v176
	v_lshlrev_b32_e32 v90, 16, v177
	v_and_b32_e32 v91, 0xffff0000, v177
	v_lshlrev_b32_e32 v84, 16, v174
	v_and_b32_e32 v85, 0xffff0000, v174
	v_lshlrev_b32_e32 v86, 16, v175
	v_and_b32_e32 v87, 0xffff0000, v175
	v_lshlrev_b32_e32 v80, 16, v172
	v_and_b32_e32 v81, 0xffff0000, v172
	v_lshlrev_b32_e32 v82, 16, v173
	v_and_b32_e32 v83, 0xffff0000, v173
	v_lshlrev_b32_e32 v76, 16, v170
	v_and_b32_e32 v77, 0xffff0000, v170
	v_lshlrev_b32_e32 v78, 16, v171
	v_and_b32_e32 v79, 0xffff0000, v171
	v_lshlrev_b32_e32 v72, 16, v168
	v_and_b32_e32 v73, 0xffff0000, v168
	v_lshlrev_b32_e32 v74, 16, v169
	v_and_b32_e32 v75, 0xffff0000, v169
	v_lshlrev_b32_e32 v68, 16, v166
	v_and_b32_e32 v69, 0xffff0000, v166
	v_lshlrev_b32_e32 v70, 16, v167
	v_and_b32_e32 v71, 0xffff0000, v167
	v_lshlrev_b32_e32 v64, 16, v164
	v_and_b32_e32 v65, 0xffff0000, v164
	v_lshlrev_b32_e32 v66, 16, v165
	v_and_b32_e32 v67, 0xffff0000, v165
	s_branch .LBB0_65

; __device__ __forceinline__ void glds16(const void*gsrc,unsigned lds_dst){unsigned keep;
;   asm volatile("s_mov_b32 %0, m0\n\ts_mov_b32 m0, %2\n\ts_nop 0\n\tglobal_load_lds_dwordx4 %1, off\n\ts_mov_b32 m0, %0":"=&s"(keep):"v"(gsrc),"s"(lds_dst):"memory");}
.LBB0_381:
	s_waitcnt lgkmcnt(7)
	v_mfma_f32_32x32x16_bf16 v[96:111], v[184:187], v[156:159], v[64:79]
	s_add_i32 s34, s50, s55
	v_lshl_add_u64 v[210:211], v[208:209], 0, s[40:41]
	v_add_u32_e32 v120, s94, v216
	s_waitcnt lgkmcnt(6)
	v_mfma_f32_32x32x16_bf16 v[80:95], v[188:191], v[156:159], v[64:79]
	v_lshl_add_u64 v[188:189], v[204:205], 0, s[40:41]
	v_lshl_add_u64 v[116:117], v[188:189], 0, s[26:27]
	s_mov_b32 m0, s34
	s_nop 0
	global_load_lds_dwordx4 v[116:117], off
	s_add_i32 s34, s49, 0xffffc000
	v_lshl_add_u64 v[190:191], v[206:207], 0, s[40:41]
	s_and_b32 s34, s34, 0xc000
	v_lshl_add_u64 v[116:117], v[190:191], 0, s[24:25]
	s_waitcnt lgkmcnt(5)
	v_mfma_f32_32x32x16_bf16 v[96:111], v[180:183], v[152:155], v[96:111]
	s_add_i32 s34, s34, s56
	s_mov_b32 m0, s34
	s_nop 0
	global_load_lds_dwordx4 v[116:117], off
	v_lshl_add_u64 v[116:117], v[210:211], 0, s[24:25]
	s_addk_i32 s34, 0x2000
	s_mov_b32 m0, s34
	s_nop 0
	global_load_lds_dwordx4 v[116:117], off
	s_waitcnt lgkmcnt(4)
	v_mfma_f32_32x32x16_bf16 v[80:95], v[176:179], v[152:155], v[80:95]
	s_waitcnt lgkmcnt(3)
	v_mfma_f32_32x32x16_bf16 v[96:111], v[172:175], v[148:151], v[96:111]
	s_waitcnt lgkmcnt(2)
	v_mfma_f32_32x32x16_bf16 v[80:95], v[168:171], v[148:151], v[80:95]
	s_waitcnt lgkmcnt(1)
	v_mfma_f32_32x32x16_bf16 v[96:111], v[164:167], v[144:147], v[96:111]
	s_waitcnt lgkmcnt(0)
	v_mfma_f32_32x32x16_bf16 v[80:95], v[160:163], v[144:147], v[80:95]
	ds_read_b128 v[116:119], v120
	ds_read_b128 v[184:187], v120 offset:512
	ds_read_b128 v[180:183], v120 offset:2048
	ds_read_b128 v[176:179], v120 offset:2560
	ds_read_b128 v[160:163], v120 offset:4096
	ds_read_b128 v[164:167], v120 offset:4608
	ds_read_b128 v[168:171], v120 offset:6144
	ds_read_b128 v[172:175], v120 offset:6656
.LBB0_382:
	s_and_b32 s46, s49, 0xc000
	v_add_u32_e32 v238, s46, v199
	ds_read_b64_tr_b16 v[120:121],v238 offset:0
	ds_read_b64_tr_b16 v[122:123],v238 offset:512
	ds_read_b64_tr_b16 v[124:125],v238 offset:4096
	ds_read_b64_tr_b16 v[126:127],v238 offset:4608
	ds_read_b64_tr_b16 v[136:137],v238 offset:8192
	ds_read_b64_tr_b16 v[138:139],v238 offset:8704
	ds_read_b64_tr_b16 v[140:141],v238 offset:12288
	ds_read_b64_tr_b16 v[142:143],v238 offset:12800
	ds_read_b64_tr_b16 v[222:223],v238 offset:1024
	ds_read_b64_tr_b16 v[224:225],v238 offset:1536
	ds_read_b64_tr_b16 v[226:227],v238 offset:5120
	ds_read_b64_tr_b16 v[228:229],v238 offset:5632
	ds_read_b64_tr_b16 v[230:231],v238 offset:9216
	ds_read_b64_tr_b16 v[232:233],v238 offset:9728
	ds_read_b64_tr_b16 v[234:235],v238 offset:13312
	ds_read_b64_tr_b16 v[236:237],v238 offset:13824
	s_waitcnt lgkmcnt(8)
	s_nop 0
	v_mfma_f32_32x32x16_bf16 v[48:63], v[192:195], v[120:123], v[48:63]
	v_exp_f32_e32 v96, v96
	v_exp_f32_e32 v97, v97
	v_mfma_f32_32x32x16_bf16 v[32:47], v[192:195], v[124:127], v[32:47]
	v_exp_f32_e32 v98, v98
	v_exp_f32_e32 v99, v99
	v_add_f32_e32 v120, v96, v98
	v_add_f32_e32 v121, v97, v99
	v_mfma_f32_32x32x16_bf16 v[16:31], v[192:195], v[136:139], v[16:31]
	v_exp_f32_e32 v100, v100
	v_exp_f32_e32 v101, v101
	v_add_f32_e32 v120, v120, v100
	v_add_f32_e32 v121, v121, v101
	v_mfma_f32_32x32x16_bf16 v[0:15], v[192:195], v[140:143], v[0:15]
	v_exp_f32_e32 v102, v102
	v_exp_f32_e32 v103, v103
	v_add_f32_e32 v239, v120, v102
	v_add_f32_e32 v240, v121, v103
	ds_read_b64_tr_b16 v[120:121],v238 offset:2048
	ds_read_b64_tr_b16 v[122:123],v238 offset:2560
	ds_read_b64_tr_b16 v[124:125],v238 offset:6144
	ds_read_b64_tr_b16 v[126:127],v238 offset:6656
	ds_read_b64_tr_b16 v[136:137],v238 offset:10240
	ds_read_b64_tr_b16 v[138:139],v238 offset:10752
	ds_read_b64_tr_b16 v[140:141],v238 offset:14336
	ds_read_b64_tr_b16 v[142:143],v238 offset:14848
	s_waitcnt lgkmcnt(8)
	v_mfma_f32_32x32x16_bf16 v[48:63], v[132:135], v[222:225], v[48:63]
	v_exp_f32_e32 v104, v104
	v_exp_f32_e32 v105, v105
	v_add_f32_e32 v192, v239, v104
	v_add_f32_e32 v193, v240, v105
	v_mfma_f32_32x32x16_bf16 v[32:47], v[132:135], v[226:229], v[32:47]
	v_exp_f32_e32 v106, v106
	v_exp_f32_e32 v107, v107
	v_add_f32_e32 v192, v192, v106
	v_add_f32_e32 v193, v193, v107
	v_mfma_f32_32x32x16_bf16 v[16:31], v[132:135], v[230:233], v[16:31]
	v_exp_f32_e32 v108, v108
	v_exp_f32_e32 v109, v109
	v_add_f32_e32 v192, v192, v108
	v_add_f32_e32 v193, v193, v109
	v_mfma_f32_32x32x16_bf16 v[0:15], v[132:135], v[234:237], v[0:15]
	v_exp_f32_e32 v110, v110
	v_exp_f32_e32 v111, v111
	v_add_f32_e32 v230, v192, v110
	v_add_f32_e32 v231, v193, v111
	ds_read_b64_tr_b16 v[132:133],v238 offset:3072
	ds_read_b64_tr_b16 v[134:135],v238 offset:3584
	ds_read_b64_tr_b16 v[192:193],v238 offset:7168
	ds_read_b64_tr_b16 v[194:195],v238 offset:7680
	ds_read_b64_tr_b16 v[222:223],v238 offset:11264
	ds_read_b64_tr_b16 v[224:225],v238 offset:11776
	ds_read_b64_tr_b16 v[226:227],v238 offset:15360
	ds_read_b64_tr_b16 v[228:229],v238 offset:15872
	s_waitcnt lgkmcnt(8)
	v_mfma_f32_32x32x16_bf16 v[48:63], v[128:131], v[120:123], v[48:63]
	v_exp_f32_e32 v80, v80
	v_exp_f32_e32 v81, v81
	v_add_f32_e32 v230, v80, v230
	v_add_f32_e32 v231, v81, v231
	v_mfma_f32_32x32x16_bf16 v[32:47], v[128:131], v[124:127], v[32:47]
	v_exp_f32_e32 v82, v82
	v_exp_f32_e32 v83, v83
	v_add_f32_e32 v120, v230, v82
	v_add_f32_e32 v121, v231, v83
	v_mfma_f32_32x32x16_bf16 v[16:31], v[128:131], v[136:139], v[16:31]
	v_exp_f32_e32 v84, v84
	v_exp_f32_e32 v85, v85
	v_add_f32_e32 v120, v120, v84
	v_add_f32_e32 v121, v121, v85
	v_mfma_f32_32x32x16_bf16 v[0:15], v[128:131], v[140:143], v[0:15]
	v_exp_f32_e32 v86, v86
	v_exp_f32_e32 v87, v87
	v_add_f32_e32 v120, v120, v86
	v_add_f32_e32 v121, v121, v87
	s_waitcnt lgkmcnt(0)
	v_mfma_f32_32x32x16_bf16 v[48:63], v[112:115], v[132:135], v[48:63]
	v_exp_f32_e32 v88, v88
	v_exp_f32_e32 v89, v89
	v_add_f32_e32 v120, v120, v88
	v_add_f32_e32 v121, v121, v89
	v_mfma_f32_32x32x16_bf16 v[32:47], v[112:115], v[192:195], v[32:47]
	v_exp_f32_e32 v90, v90
	v_exp_f32_e32 v91, v91
	v_add_f32_e32 v120, v120, v90
	v_add_f32_e32 v121, v121, v91
	v_mfma_f32_32x32x16_bf16 v[16:31], v[112:115], v[222:225], v[16:31]
	v_exp_f32_e32 v92, v92
	v_exp_f32_e32 v93, v93
	v_add_f32_e32 v120, v120, v92
	v_add_f32_e32 v121, v121, v93
	v_mfma_f32_32x32x16_bf16 v[0:15], v[112:115], v[226:229], v[0:15]
	v_exp_f32_e32 v94, v94
	v_exp_f32_e32 v95, v95
	v_add_f32_e32 v192, v120, v94
	v_add_f32_e32 v193, v121, v95
	v_add_f32_e32 v120, v192, v193
	v_cmp_lt_f32_e32 vcc, 0x44800000, v120
	s_cbranch_vccnz .Lattn_rare1
; __device__ __forceinline__ void cmask(f32x16&p0,f32x16&p1,int jb,int qrel,int hi,lds_cfptr bt){
;   const float NEG=-INFINITY;
;     ...
;   const int kb=64*jb+4*hi; const int qlim=(qrel|63)-kb; const int base=kb-qrel+128;
;   #pragma unroll
;   for(int r=0;r<16;++r){const int ko=(r&3)+8*(r>>2);
;     const float b0=bt[med3i(base+ko,0,192)], b1=bt[med3i(base+ko+32,0,192)];
;     p0[r]=(ko>qlim)?NEG:p0[r]+b0; p1[r]=(ko+32>qlim)?NEG:p1[r]+b1;
;     if((r%CM_GRP)==CM_GRP-1)__builtin_amdgcn_sched_barrier(0); }
.LBB0_384:
	s_waitcnt lgkmcnt(7)
	v_mfma_f32_32x32x16_bf16 v[128:143], v[116:119], v[156:159], v[64:79]
	s_add_i32 s34, s94, 0x2000
	s_mov_b64 s[44:45], 0xa0000
	s_waitcnt vmcnt(3) lgkmcnt(0)
	s_barrier
	s_cmpk_lg_i32 s94, 0x4000
	s_cselect_b32 s50, s34, 0
	s_add_i32 s34, s94, s55
	s_waitcnt lgkmcnt(6)
	v_mfma_f32_32x32x16_bf16 v[112:127], v[184:187], v[156:159], v[64:79]
	s_waitcnt lgkmcnt(5)
	v_mfma_f32_32x32x16_bf16 v[128:143], v[180:183], v[152:155], v[128:143]
	s_waitcnt lgkmcnt(4)
	v_mfma_f32_32x32x16_bf16 v[112:127], v[176:179], v[152:155], v[112:127]
	s_waitcnt lgkmcnt(3)
	v_mfma_f32_32x32x16_bf16 v[128:143], v[160:163], v[148:151], v[128:143]
	v_lshl_add_u64 v[160:161], v[188:189], 0, s[44:45]
	s_mov_b32 m0, s34
	s_nop 0
	global_load_lds_dwordx4 v[160:161], off
	v_lshl_add_u64 v[160:161], v[190:191], 0, s[26:27]
	s_add_i32 s34, s46, s56
	s_mov_b32 m0, s34
	s_nop 0
	global_load_lds_dwordx4 v[160:161], off
	v_lshl_add_u64 v[160:161], v[210:211], 0, s[26:27]
	s_addk_i32 s34, 0x2000
	s_waitcnt lgkmcnt(2)
	v_mfma_f32_32x32x16_bf16 v[112:127], v[164:167], v[148:151], v[112:127]
	s_mov_b32 m0, s34
	s_nop 0
	global_load_lds_dwordx4 v[160:161], off
	v_add_u32_e32 v160, s50, v216
	s_add_i32 s34, s48, s42
	s_cmp_lt_i32 s34, -7
	s_waitcnt lgkmcnt(1)
	v_mfma_f32_32x32x16_bf16 v[128:143], v[168:171], v[144:147], v[128:143]
	s_waitcnt lgkmcnt(0)
	v_mfma_f32_32x32x16_bf16 v[112:127], v[172:175], v[144:147], v[112:127]
	ds_read_b128 v[184:187], v160
	ds_read_b128 v[188:191], v160 offset:512
	ds_read_b128 v[180:183], v160 offset:2048
	ds_read_b128 v[176:179], v160 offset:2560
	ds_read_b128 v[172:175], v160 offset:4096
	ds_read_b128 v[168:171], v160 offset:4608
	ds_read_b128 v[164:167], v160 offset:6144
	ds_read_b128 v[160:163], v160 offset:6656
	s_cbranch_scc1 .LBB0_386
	v_subrev_u32_e32 v194, 27, v219
	v_med3_i32 v195, v194, 0, v212
	v_max_i32_e32 v194, 0xffffffe0, v194
	v_add_u32_e32 v194, 32, v194
	v_min_u32_e32 v194, 0xc0, v194
	v_lshl_add_u32 v210, v194, 2, s15
	v_subrev_u32_e32 v194, 26, v219
	v_med3_i32 v211, v194, 0, v212
	v_max_i32_e32 v194, 0xffffffe0, v194
	v_add_u32_e32 v194, 32, v194
	v_min_u32_e32 v194, 0xc0, v194
	v_lshl_add_u32 v222, v194, 2, s15
	v_subrev_u32_e32 v194, 25, v219
	v_med3_i32 v223, v194, 0, v212
	v_max_i32_e32 v194, 0xffffffe0, v194
	v_add_u32_e32 v194, 32, v194
	v_min_u32_e32 v194, 0xc0, v194
	v_lshl_add_u32 v224, v194, 2, s15
	v_subrev_u32_e32 v194, 24, v219
	v_med3_i32 v225, v194, 0, v212
	v_max_i32_e32 v194, 0xffffffe0, v194
	v_add_u32_e32 v194, 32, v194
	v_min_u32_e32 v194, 0xc0, v194
	v_lshl_add_u32 v195, v195, 2, s15
	v_lshl_add_u32 v211, v211, 2, s15
	v_lshl_add_u32 v223, v223, 2, s15
	v_lshl_add_u32 v225, v225, 2, s15
	v_lshl_add_u32 v226, v194, 2, s15
	ds_read_b32 v194, v195
	ds_read_b32 v210, v210
	ds_read_b32 v195, v211
	ds_read_b32 v211, v222
	ds_read_b32 v222, v223
	ds_read_b32 v224, v224
	ds_read_b32 v223, v225
	ds_read_b32 v225, v226
	v_subrev_u32_e32 v226, 19, v219
	v_med3_i32 v227, v226, 0, v212
	v_max_i32_e32 v226, 0xffffffe0, v226
	v_add_u32_e32 v226, 32, v226
	v_min_u32_e32 v226, 0xc0, v226
	v_lshl_add_u32 v228, v226, 2, s15
	v_subrev_u32_e32 v226, 18, v219
	v_med3_i32 v229, v226, 0, v212
	v_max_i32_e32 v226, 0xffffffe0, v226
	v_add_u32_e32 v226, 32, v226
	v_min_u32_e32 v226, 0xc0, v226
	v_lshl_add_u32 v230, v226, 2, s15
	v_subrev_u32_e32 v226, 17, v219
	v_med3_i32 v231, v226, 0, v212
	v_max_i32_e32 v226, 0xffffffe0, v226
	v_add_u32_e32 v226, 32, v226
	v_min_u32_e32 v226, 0xc0, v226
	v_lshl_add_u32 v232, v226, 2, s15
	v_add_u32_e32 v226, -16, v219
	v_med3_i32 v233, v226, 0, v212
	v_max_i32_e32 v226, 0xffffffe0, v226
	v_add_u32_e32 v226, 32, v226
	v_min_u32_e32 v226, 0xc0, v226
	v_lshl_add_u32 v227, v227, 2, s15
	v_lshl_add_u32 v229, v229, 2, s15
	v_lshl_add_u32 v231, v231, 2, s15
	v_lshl_add_u32 v233, v233, 2, s15
	v_lshl_add_u32 v234, v226, 2, s15
	ds_read_b32 v226, v227
	ds_read_b32 v228, v228
	ds_read_b32 v227, v229
	ds_read_b32 v229, v230
	ds_read_b32 v230, v231
	ds_read_b32 v232, v232
	ds_read_b32 v231, v233
	ds_read_b32 v233, v234
	v_add_u32_e32 v234, -11, v219
	v_med3_i32 v235, v234, 0, v212
	v_max_i32_e32 v234, 0xffffffe0, v234
	v_add_u32_e32 v234, 32, v234
	v_min_u32_e32 v234, 0xc0, v234
	v_lshl_add_u32 v236, v234, 2, s15
	v_add_u32_e32 v234, -10, v219
	v_med3_i32 v237, v234, 0, v212
	v_max_i32_e32 v234, 0xffffffe0, v234
	v_add_u32_e32 v234, 32, v234
	v_min_u32_e32 v234, 0xc0, v234
	v_lshl_add_u32 v238, v234, 2, s15
	v_add_u32_e32 v234, -9, v219
	v_med3_i32 v239, v234, 0, v212
	v_max_i32_e32 v234, 0xffffffe0, v234
	v_add_u32_e32 v234, 32, v234
	v_min_u32_e32 v234, 0xc0, v234
	v_lshl_add_u32 v240, v234, 2, s15
	v_add_u32_e32 v234, -8, v219
	v_med3_i32 v241, v234, 0, v212
	v_max_i32_e32 v234, 0xffffffe0, v234
	v_add_u32_e32 v234, 32, v234
	v_min_u32_e32 v234, 0xc0, v234
	v_lshl_add_u32 v235, v235, 2, s15
	v_lshl_add_u32 v237, v237, 2, s15
	v_lshl_add_u32 v239, v239, 2, s15
	v_lshl_add_u32 v241, v241, 2, s15
	v_lshl_add_u32 v242, v234, 2, s15
	ds_read_b32 v234, v235
	ds_read_b32 v236, v236
	ds_read_b32 v235, v237
	ds_read_b32 v237, v238
	ds_read_b32 v238, v239
	ds_read_b32 v240, v240
	ds_read_b32 v239, v241
	ds_read_b32 v241, v242
	v_add_u32_e32 v242, -3, v219
	v_med3_i32 v243, v242, 0, v212
	v_max_i32_e32 v242, 0xffffffe0, v242
	v_add_u32_e32 v242, 32, v242
	v_min_u32_e32 v242, 0xc0, v242
	v_lshl_add_u32 v244, v242, 2, s15
	v_add_u32_e32 v242, -2, v219
	v_med3_i32 v245, v242, 0, v212
	v_max_i32_e32 v242, 0xffffffe0, v242
	v_add_u32_e32 v242, 32, v242
	v_min_u32_e32 v242, 0xc0, v242
	v_lshl_add_u32 v246, v242, 2, s15
	v_add_u32_e32 v242, -1, v219
	v_med3_i32 v247, v242, 0, v212
	v_max_i32_e32 v242, 0xffffffe0, v242
	v_add_u32_e32 v242, 32, v242
	v_min_u32_e32 v242, 0xc0, v242
	v_lshl_add_u32 v248, v242, 2, s15
	v_med3_i32 v242, v219, 0, v212
	v_lshl_add_u32 v249, v242, 2, s15
	v_max_i32_e32 v242, 0xffffffe0, v219
	v_add_u32_e32 v242, 32, v242
	v_lshl_add_u32 v243, v243, 2, s15
	v_lshl_add_u32 v245, v245, 2, s15
	v_lshl_add_u32 v247, v247, 2, s15
	v_min_u32_e32 v242, 0xc0, v242
	v_lshl_add_u32 v250, v242, 2, s15
	ds_read_b32 v242, v243
	ds_read_b32 v244, v244
	ds_read_b32 v243, v245
	ds_read_b32 v245, v246
	ds_read_b32 v246, v247
	ds_read_b32 v248, v248
	ds_read_b32 v247, v249
	ds_read_b32 v249, v250
	v_cmp_lt_i32_e32 vcc, 26, v220
	s_waitcnt lgkmcnt(5)
; __device__ __forceinline__ void cmask(f32x16&p0,f32x16&p1,int jb,int qrel,int hi,lds_cfptr bt){
;     ...
;   const int kb=64*jb+4*hi; const int qlim=(qrel|63)-kb; const int base=kb-qrel+128;
;   #pragma unroll
;   for(int r=0;r<16;++r){const int ko=(r&3)+8*(r>>2);
;     const float b0=bt[med3i(base+ko,0,192)], b1=bt[med3i(base+ko+32,0,192)];
;     p0[r]=(ko>qlim)?NEG:p0[r]+b0; p1[r]=(ko+32>qlim)?NEG:p1[r]+b1;
;     if((r%CM_GRP)==CM_GRP-1)__builtin_amdgcn_sched_barrier(0); }
	v_pk_add_f32 v[140:141], v[140:141], v[242:243]
	v_pk_add_f32 v[138:139], v[138:139], v[238:239]
	s_waitcnt lgkmcnt(1)
	v_pk_add_f32 v[142:143], v[142:143], v[246:247]
	v_pk_add_f32 v[136:137], v[136:137], v[234:235]
	v_cndmask_b32_e32 v143, v213, v143, vcc
	v_cmp_lt_i32_e32 vcc, 25, v220
	v_pk_add_f32 v[134:135], v[134:135], v[230:231]
	v_pk_add_f32 v[132:133], v[132:133], v[226:227]
	v_cndmask_b32_e32 v142, v213, v142, vcc
	v_cmp_lt_i32_e32 vcc, 24, v220
	v_pk_add_f32 v[130:131], v[130:131], v[222:223]
	v_pk_add_f32 v[128:129], v[128:129], v[194:195]
	v_cndmask_b32_e32 v141, v213, v141, vcc
	v_cmp_lt_i32_e32 vcc, 23, v220
	s_waitcnt lgkmcnt(0)
	v_pk_add_f32 v[126:127], v[126:127], v[248:249]
	v_pk_add_f32 v[124:125], v[124:125], v[244:245]
	v_cndmask_b32_e32 v140, v213, v140, vcc
	v_cmp_lt_i32_e32 vcc, 18, v220
	v_pk_add_f32 v[122:123], v[122:123], v[240:241]
	v_pk_add_f32 v[120:121], v[120:121], v[236:237]
	v_cndmask_b32_e32 v139, v213, v139, vcc
	v_cmp_lt_i32_e32 vcc, 17, v220
	v_pk_add_f32 v[118:119], v[118:119], v[232:233]
	v_pk_add_f32 v[116:117], v[116:117], v[228:229]
	v_cndmask_b32_e32 v138, v213, v138, vcc
	v_cmp_lt_i32_e32 vcc, 16, v220
	v_pk_add_f32 v[114:115], v[114:115], v[224:225]
	v_pk_add_f32 v[112:113], v[112:113], v[210:211]
	v_cndmask_b32_e32 v137, v213, v137, vcc
	v_cmp_lt_i32_e32 vcc, 15, v220
	s_nop 1
	v_cndmask_b32_e32 v136, v213, v136, vcc
	v_cmp_lt_i32_e32 vcc, 10, v220
	s_nop 1
	v_cndmask_b32_e32 v135, v213, v135, vcc
	v_cmp_lt_i32_e32 vcc, 9, v220
	s_nop 1
	v_cndmask_b32_e32 v134, v213, v134, vcc
	v_cmp_lt_i32_e32 vcc, 8, v220
	s_nop 1
	v_cndmask_b32_e32 v133, v213, v133, vcc
	v_cmp_lt_i32_e32 vcc, 7, v220
	s_nop 1
	v_cndmask_b32_e32 v132, v213, v132, vcc
	v_cmp_lt_i32_e32 vcc, 2, v220
	s_nop 1
	v_cndmask_b32_e32 v131, v213, v131, vcc
	v_cmp_lt_i32_e32 vcc, 1, v220
	s_nop 1
	v_cndmask_b32_e32 v130, v213, v130, vcc
	v_cmp_lt_i32_e32 vcc, 0, v220
	s_nop 1
	v_cndmask_b32_e32 v129, v213, v129, vcc
	v_cmp_lt_i32_e32 vcc, -1, v220
	s_nop 1
	v_cndmask_b32_e32 v128, v213, v128, vcc
	v_cmp_lt_i32_e32 vcc, 58, v220
	s_nop 1
	v_cndmask_b32_e32 v127, v213, v127, vcc
	v_cmp_lt_i32_e32 vcc, 57, v220
	s_nop 1
	v_cndmask_b32_e32 v126, v213, v126, vcc
	v_cmp_lt_i32_e32 vcc, 56, v220
	s_nop 1
	v_cndmask_b32_e32 v125, v213, v125, vcc
	v_cmp_lt_i32_e32 vcc, 55, v220
	s_nop 1
	v_cndmask_b32_e32 v124, v213, v124, vcc
	v_cmp_lt_i32_e32 vcc, 50, v220
	s_nop 1
	v_cndmask_b32_e32 v123, v213, v123, vcc
	v_cmp_lt_i32_e32 vcc, 49, v220
	s_nop 1
	v_cndmask_b32_e32 v122, v213, v122, vcc
	v_cmp_lt_i32_e32 vcc, 48, v220
	s_nop 1
	v_cndmask_b32_e32 v121, v213, v121, vcc
	v_cmp_lt_i32_e32 vcc, 47, v220
	s_nop 1
	v_cndmask_b32_e32 v120, v213, v120, vcc
	v_cmp_lt_i32_e32 vcc, 42, v220
	s_nop 1
	v_cndmask_b32_e32 v119, v213, v119, vcc
	v_cmp_lt_i32_e32 vcc, 41, v220
	s_nop 1
	v_cndmask_b32_e32 v118, v213, v118, vcc
	v_cmp_lt_i32_e32 vcc, 40, v220
	s_nop 1
	v_cndmask_b32_e32 v117, v213, v117, vcc
	v_cmp_lt_i32_e32 vcc, 39, v220
	s_nop 1
	v_cndmask_b32_e32 v116, v213, v116, vcc
	v_cmp_lt_i32_e32 vcc, 34, v220
	s_nop 1
	v_cndmask_b32_e32 v115, v213, v115, vcc
	v_cmp_lt_i32_e32 vcc, 33, v220
	s_nop 1
	v_cndmask_b32_e32 v114, v213, v114, vcc
	v_cmp_lt_i32_e32 vcc, 32, v220
	s_nop 1
	v_cndmask_b32_e32 v113, v213, v113, vcc
	v_cmp_lt_i32_e32 vcc, 31, v220
	s_nop 1
	v_cndmask_b32_e32 v112, v213, v112, vcc

.LBB0_387:
	s_add_i32 s34, s49, 0xffff4000
	s_and_b32 s34, s34, 0xc000
	v_cvt_pk_bf16_f32 v222, v96, v97
	v_cvt_pk_bf16_f32 v223, v98, v99
	v_cvt_pk_bf16_f32 v224, v100, v101
	v_cvt_pk_bf16_f32 v225, v102, v103
	v_cvt_pk_bf16_f32 v100, v104, v105
	v_cvt_pk_bf16_f32 v101, v106, v107
	v_cvt_pk_bf16_f32 v102, v108, v109
	v_cvt_pk_bf16_f32 v103, v110, v111
	v_cvt_pk_bf16_f32 v96, v80, v81
	v_cvt_pk_bf16_f32 v97, v82, v83
	v_cvt_pk_bf16_f32 v98, v84, v85
	v_cvt_pk_bf16_f32 v99, v86, v87
	v_cvt_pk_bf16_f32 v80, v88, v89
	v_cvt_pk_bf16_f32 v81, v90, v91
	v_cvt_pk_bf16_f32 v82, v92, v93
	v_cvt_pk_bf16_f32 v83, v94, v95
	v_add_u32_e32 v193, s34, v199
	ds_read_b64_tr_b16 v[84:85],v193 offset:0
	ds_read_b64_tr_b16 v[86:87],v193 offset:512
	ds_read_b64_tr_b16 v[88:89],v193 offset:4096
	ds_read_b64_tr_b16 v[90:91],v193 offset:4608
	ds_read_b64_tr_b16 v[92:93],v193 offset:8192
	ds_read_b64_tr_b16 v[94:95],v193 offset:8704
	ds_read_b64_tr_b16 v[104:105],v193 offset:12288
	ds_read_b64_tr_b16 v[106:107],v193 offset:12800
	ds_read_b64_tr_b16 v[108:109],v193 offset:1024
	ds_read_b64_tr_b16 v[110:111],v193 offset:1536
	ds_read_b64_tr_b16 v[226:227],v193 offset:5120
	ds_read_b64_tr_b16 v[228:229],v193 offset:5632
	ds_read_b64_tr_b16 v[230:231],v193 offset:9216
	ds_read_b64_tr_b16 v[232:233],v193 offset:9728
	ds_read_b64_tr_b16 v[234:235],v193 offset:13312
	ds_read_b64_tr_b16 v[236:237],v193 offset:13824
	s_waitcnt lgkmcnt(8)
	s_nop 0
	v_mfma_f32_32x32x16_bf16 v[48:63], v[222:225], v[84:87], v[48:63]
	v_exp_f32_e32 v128, v128
	v_exp_f32_e32 v129, v129
	v_mfma_f32_32x32x16_bf16 v[32:47], v[222:225], v[88:91], v[32:47]
	v_exp_f32_e32 v130, v130
	v_exp_f32_e32 v131, v131
	v_add_f32_e32 v84, v128, v130
	v_add_f32_e32 v85, v129, v131
	v_mfma_f32_32x32x16_bf16 v[16:31], v[222:225], v[92:95], v[16:31]
	v_exp_f32_e32 v132, v132
	v_exp_f32_e32 v133, v133
	v_add_f32_e32 v84, v84, v132
	v_add_f32_e32 v85, v85, v133
	v_mfma_f32_32x32x16_bf16 v[0:15], v[222:225], v[104:107], v[0:15]
	v_exp_f32_e32 v134, v134
	v_exp_f32_e32 v135, v135
	v_add_f32_e32 v194, v84, v134
	v_add_f32_e32 v195, v85, v135
	ds_read_b64_tr_b16 v[84:85],v193 offset:2048
	ds_read_b64_tr_b16 v[86:87],v193 offset:2560
	ds_read_b64_tr_b16 v[88:89],v193 offset:6144
	ds_read_b64_tr_b16 v[90:91],v193 offset:6656
	ds_read_b64_tr_b16 v[92:93],v193 offset:10240
	ds_read_b64_tr_b16 v[94:95],v193 offset:10752
	ds_read_b64_tr_b16 v[104:105],v193 offset:14336
	ds_read_b64_tr_b16 v[106:107],v193 offset:14848
	s_waitcnt lgkmcnt(8)
	v_mfma_f32_32x32x16_bf16 v[48:63], v[100:103], v[108:111], v[48:63]
	v_exp_f32_e32 v136, v136
	v_exp_f32_e32 v137, v137
	v_add_f32_e32 v194, v194, v136
	v_add_f32_e32 v195, v195, v137
	v_mfma_f32_32x32x16_bf16 v[32:47], v[100:103], v[226:229], v[32:47]
	v_exp_f32_e32 v138, v138
	v_exp_f32_e32 v139, v139
	v_add_f32_e32 v108, v194, v138
	v_add_f32_e32 v109, v195, v139
	v_mfma_f32_32x32x16_bf16 v[16:31], v[100:103], v[230:233], v[16:31]
	v_exp_f32_e32 v140, v140
	v_exp_f32_e32 v141, v141
	v_add_f32_e32 v108, v108, v140
	v_add_f32_e32 v109, v109, v141
	v_mfma_f32_32x32x16_bf16 v[0:15], v[100:103], v[234:237], v[0:15]
	v_exp_f32_e32 v142, v142
	v_exp_f32_e32 v143, v143
	v_add_f32_e32 v194, v108, v142
	v_add_f32_e32 v195, v109, v143
	ds_read_b64_tr_b16 v[100:101],v193 offset:3072
	ds_read_b64_tr_b16 v[102:103],v193 offset:3584
	ds_read_b64_tr_b16 v[108:109],v193 offset:7168
	ds_read_b64_tr_b16 v[110:111],v193 offset:7680
	ds_read_b64_tr_b16 v[222:223],v193 offset:11264
	ds_read_b64_tr_b16 v[224:225],v193 offset:11776
	ds_read_b64_tr_b16 v[226:227],v193 offset:15360
	ds_read_b64_tr_b16 v[228:229],v193 offset:15872
	s_waitcnt lgkmcnt(8)
	v_mfma_f32_32x32x16_bf16 v[48:63], v[96:99], v[84:87], v[48:63]
	v_exp_f32_e32 v112, v112
	v_exp_f32_e32 v113, v113
	v_add_f32_e32 v193, v112, v194
	v_add_f32_e32 v194, v113, v195
	v_mfma_f32_32x32x16_bf16 v[32:47], v[96:99], v[88:91], v[32:47]
	v_exp_f32_e32 v114, v114
	v_exp_f32_e32 v115, v115
	v_add_f32_e32 v84, v193, v114
	v_add_f32_e32 v85, v194, v115
	v_mfma_f32_32x32x16_bf16 v[16:31], v[96:99], v[92:95], v[16:31]
	v_exp_f32_e32 v116, v116
	v_exp_f32_e32 v117, v117
	v_add_f32_e32 v84, v84, v116
	v_add_f32_e32 v85, v85, v117
	v_mfma_f32_32x32x16_bf16 v[0:15], v[96:99], v[104:107], v[0:15]
	v_exp_f32_e32 v118, v118
	v_exp_f32_e32 v119, v119
	v_add_f32_e32 v84, v84, v118
	v_add_f32_e32 v85, v85, v119
	s_waitcnt lgkmcnt(0)
	v_mfma_f32_32x32x16_bf16 v[48:63], v[80:83], v[100:103], v[48:63]
	v_exp_f32_e32 v120, v120
	v_exp_f32_e32 v121, v121
	v_add_f32_e32 v84, v84, v120
	v_add_f32_e32 v85, v85, v121
	v_mfma_f32_32x32x16_bf16 v[32:47], v[80:83], v[108:111], v[32:47]
	v_exp_f32_e32 v122, v122
	v_exp_f32_e32 v123, v123
	v_add_f32_e32 v84, v84, v122
	v_add_f32_e32 v85, v85, v123
	v_mfma_f32_32x32x16_bf16 v[16:31], v[80:83], v[222:225], v[16:31]
	v_exp_f32_e32 v124, v124
	v_exp_f32_e32 v125, v125
	v_add_f32_e32 v84, v84, v124
	v_add_f32_e32 v85, v85, v125
	v_mfma_f32_32x32x16_bf16 v[0:15], v[80:83], v[226:229], v[0:15]
	v_exp_f32_e32 v126, v126
	v_exp_f32_e32 v127, v127
	v_add_f32_e32 v84, v84, v126
	v_add_f32_e32 v85, v85, v127
	v_add_f32_e32 v80, v84, v85
	v_cmp_lt_f32_e32 vcc, 0x44800000, v80
	s_cbranch_vccz .LBB0_380
	v_max3_f32 v86, v128, v129, v130
	v_max3_f32 v87, v131, v132, v133
	v_max3_f32 v86, v86, v134, v135
	v_max3_f32 v87, v87, v136, v137
	v_max3_f32 v86, v86, v138, v139
	v_max3_f32 v87, v87, v140, v141
	v_max3_f32 v86, v86, v142, v143
	v_max3_f32 v87, v87, v112, v113
	v_max3_f32 v86, v86, v114, v115
	v_max3_f32 v87, v87, v116, v117
	v_max3_f32 v86, v86, v118, v119
	v_max3_f32 v87, v87, v120, v121
	v_max3_f32 v86, v86, v122, v123
	v_max3_f32 v87, v87, v124, v125
	v_max3_f32 v86, v86, v126, v127
	v_max_f32_e32 v86, v86, v87
	v_mov_b32_e32 v87, v86
	s_nop 1
	v_permlane32_swap_b32_e32 v86, v87
	v_max_f32_e32 v86, v86, v87
	v_frexp_exp_i32_f32_e32 v87, v86
	v_max_i32_e32 v87, 0, v87
	v_sub_u32_e32 v88, 0, v87
	v_ldexp_f32 v89, 1.0, v88
	v_cvt_f32_i32_e32 v90, v87
	v_add_f32_e32 v202, v202, v90
	v_xor_b32_e32 v64, 0x80000000, v202
	v_mov_b32_e32 v65, v64
	v_mov_b32_e32 v66, v64
	v_mov_b32_e32 v67, v64
	v_mov_b32_e32 v68, v64
	v_mov_b32_e32 v69, v64
	v_mov_b32_e32 v70, v64
	v_mov_b32_e32 v71, v64
	v_mov_b32_e32 v72, v64
	v_mov_b32_e32 v73, v64
	v_mov_b32_e32 v74, v64
	v_mov_b32_e32 v75, v64
	v_mov_b32_e32 v76, v64
	v_mov_b32_e32 v77, v64
	v_mov_b32_e32 v78, v64
	v_mov_b32_e32 v79, v64
	s_and_saveexec_b64 s[44:45], s[4:5]
	ds_write_b32 v218, v89
	s_or_b64 exec, exec, s[44:45]
	v_mul_f32_e32 v128, v128, v89
	v_mul_f32_e32 v129, v129, v89
	v_mul_f32_e32 v130, v130, v89
	v_mul_f32_e32 v131, v131, v89
	v_mul_f32_e32 v132, v132, v89
	v_mul_f32_e32 v133, v133, v89
	v_mul_f32_e32 v134, v134, v89
	v_mul_f32_e32 v135, v135, v89
	v_mul_f32_e32 v136, v136, v89
	v_mul_f32_e32 v137, v137, v89
	v_mul_f32_e32 v138, v138, v89
	v_mul_f32_e32 v139, v139, v89
	v_mul_f32_e32 v140, v140, v89
	v_mul_f32_e32 v141, v141, v89
	v_mul_f32_e32 v142, v142, v89
	v_mul_f32_e32 v143, v143, v89
	v_mul_f32_e32 v112, v112, v89
	v_mul_f32_e32 v113, v113, v89
	v_mul_f32_e32 v114, v114, v89
	v_mul_f32_e32 v115, v115, v89
	v_mul_f32_e32 v116, v116, v89
	v_mul_f32_e32 v117, v117, v89
	v_mul_f32_e32 v118, v118, v89
	v_mul_f32_e32 v119, v119, v89
	v_mul_f32_e32 v120, v120, v89
	v_mul_f32_e32 v121, v121, v89
	v_mul_f32_e32 v122, v122, v89
	v_mul_f32_e32 v123, v123, v89
	v_mul_f32_e32 v124, v124, v89
	v_mul_f32_e32 v125, v125, v89
	v_mul_f32_e32 v126, v126, v89
	v_mul_f32_e32 v127, v127, v89
	v_mul_f32_e32 v84, v84, v89
	v_mul_f32_e32 v85, v85, v89
	v_mul_f32_e32 v192, v192, v89
	s_waitcnt lgkmcnt(0)
	ds_read_b128 v[80:83], v221 offset:96
	ds_read_b128 v[86:89], v221 offset:64
	ds_read_b128 v[90:93], v221 offset:32
	ds_read_b128 v[94:97], v221
	s_waitcnt lgkmcnt(3)
	v_pk_mul_f32 v[60:61], v[60:61], v[80:81]
	s_waitcnt lgkmcnt(2)
	v_pk_mul_f32 v[56:57], v[56:57], v[86:87]
	s_waitcnt lgkmcnt(1)
	v_pk_mul_f32 v[52:53], v[52:53], v[90:91]
	v_pk_mul_f32 v[62:63], v[62:63], v[82:83]
	v_pk_mul_f32 v[58:59], v[58:59], v[88:89]
	v_pk_mul_f32 v[54:55], v[54:55], v[92:93]
	s_waitcnt lgkmcnt(0)
	v_pk_mul_f32 v[50:51], v[50:51], v[96:97]
	v_pk_mul_f32 v[48:49], v[48:49], v[94:95]
	v_pk_mul_f32 v[44:45], v[44:45], v[80:81]
	v_pk_mul_f32 v[40:41], v[40:41], v[86:87]
	v_pk_mul_f32 v[36:37], v[36:37], v[90:91]
	v_pk_mul_f32 v[46:47], v[46:47], v[82:83]
	v_pk_mul_f32 v[42:43], v[42:43], v[88:89]
	v_pk_mul_f32 v[38:39], v[38:39], v[92:93]
	v_pk_mul_f32 v[34:35], v[34:35], v[96:97]
	v_pk_mul_f32 v[32:33], v[32:33], v[94:95]
	v_pk_mul_f32 v[28:29], v[28:29], v[80:81]
	v_pk_mul_f32 v[24:25], v[24:25], v[86:87]
	v_pk_mul_f32 v[20:21], v[20:21], v[90:91]
	v_pk_mul_f32 v[30:31], v[30:31], v[82:83]
	v_pk_mul_f32 v[26:27], v[26:27], v[88:89]
	v_pk_mul_f32 v[22:23], v[22:23], v[92:93]
	v_pk_mul_f32 v[18:19], v[18:19], v[96:97]
	v_pk_mul_f32 v[16:17], v[16:17], v[94:95]
	v_pk_mul_f32 v[12:13], v[12:13], v[80:81]
	v_pk_mul_f32 v[8:9], v[8:9], v[86:87]
	v_pk_mul_f32 v[4:5], v[4:5], v[90:91]
	v_pk_mul_f32 v[14:15], v[14:15], v[82:83]
	v_pk_mul_f32 v[10:11], v[10:11], v[88:89]
	v_pk_mul_f32 v[6:7], v[6:7], v[92:93]
	v_pk_mul_f32 v[2:3], v[2:3], v[96:97]
	v_pk_mul_f32 v[0:1], v[0:1], v[94:95]
	s_branch .LBB0_380

.LBB0_868:
	v_mov_b32_e32 v82, v65
	v_mov_b32_e32 v83, v69
	v_mov_b32_e32 v80, v64
	v_mov_b32_e32 v81, v68
	v_pk_mul_f32 v[82:83], v[82:83], v[82:83]
	v_mov_b32_e32 v84, v67
	v_mov_b32_e32 v85, v71
	v_pk_fma_f32 v[80:81], v[80:81], v[80:81], v[82:83]
	v_mov_b32_e32 v82, v66
	v_mov_b32_e32 v83, v70
	v_pk_mul_f32 v[84:85], v[84:85], v[84:85]
	s_lshr_b32 s0, s2, 6
	v_pk_fma_f32 v[82:83], v[82:83], v[82:83], v[84:85]
	v_pk_mul_f32 v[84:85], v[60:61], v[60:61]
	v_pk_add_f32 v[80:81], v[80:81], v[82:83]
	v_pk_mul_f32 v[82:83], v[62:63], v[62:63]
	v_pk_add_f32 v[80:81], v[80:81], v[80:81] op_sel_hi:[0,1]
	v_pk_mov_b32 v[86:87], v[84:85], v[82:83] op_sel:[1,0]
	v_mov_b32_e32 v85, v83
	v_mul_f32_e32 v80, v56, v56
	v_pk_add_f32 v[82:83], v[86:87], v[84:85]
	v_pk_fma_f32 v[84:85], v[56:57], v[56:57], v[80:81] op_sel_hi:[1,1,0]
	v_mul_f32_e32 v80, v58, v58
	v_pk_add_f32 v[82:83], v[82:83], v[82:83] op_sel_hi:[0,1]
	v_pk_fma_f32 v[86:87], v[58:59], v[58:59], v[80:81] op_sel_hi:[1,1,0]
	v_mul_f32_e32 v84, v52, v52
	v_mul_f32_e32 v86, v53, v53
	v_mul_f32_e32 v82, v54, v54
	v_mul_f32_e32 v80, v55, v55
	v_pk_add_f32 v[84:85], v[84:85], v[86:87]
	v_pk_add_f32 v[80:81], v[82:83], v[80:81]
	s_add_i32 s0, s0, 2
	s_ashr_i32 s1, s14, 14
	v_pk_add_f32 v[80:81], v[84:85], v[80:81]
	s_cmp_lt_i32 s14, 0x8000
	v_pk_add_f32 v[80:81], v[80:81], v[80:81] op_sel_hi:[0,1]
	v_pk_mul_f32 v[82:83], v[50:51], v[50:51]
	v_pk_mul_f32 v[84:85], v[48:49], v[48:49]
	s_cselect_b32 s0, s1, s0
	v_pk_mov_b32 v[86:87], v[84:85], v[82:83] op_sel:[1,0]
	v_mov_b32_e32 v85, v83
	v_mul_f32_e32 v80, v44, v44
	v_pk_add_f32 v[82:83], v[86:87], v[84:85]
	v_pk_fma_f32 v[84:85], v[44:45], v[44:45], v[80:81] op_sel_hi:[1,1,0]
	v_mul_f32_e32 v80, v46, v46
	s_ashr_i32 s1, s0, 31
	v_pk_add_f32 v[82:83], v[82:83], v[82:83] op_sel_hi:[0,1]
	v_pk_fma_f32 v[86:87], v[46:47], v[46:47], v[80:81] op_sel_hi:[1,1,0]
	s_lshl_b64 s[0:1], s[0:1], 14
	v_mul_f32_e32 v84, v42, v42
	v_mul_f32_e32 v86, v43, v43
	v_mul_f32_e32 v82, v40, v40
	v_mul_f32_e32 v80, v41, v41
	v_lshl_add_u64 v[96:97], v[14:15], 0, s[0:1]
	v_pk_add_f32 v[92:93], v[84:85], v[86:87]
	v_pk_add_f32 v[94:95], v[82:83], v[80:81]
	global_load_dwordx4 v[80:83], v[4:5], off
	v_lshl_add_u64 v[98:99], v[16:17], 0, s[0:1]
	global_load_dwordx4 v[84:87], v[96:97], off
	global_load_dwordx4 v[88:91], v[98:99], off
	global_load_dwordx4 v[220:223], v[4:5], off offset:1024
	global_load_dwordx4 v[224:227], v[98:99], off offset:1024
	global_load_dwordx4 v[228:231], v[96:97], off offset:1024
	global_load_dwordx4 v[232:235], v[4:5], off offset:2048
	global_load_dwordx4 v[236:239], v[98:99], off offset:2048
	global_load_dwordx4 v[240:243], v[96:97], off offset:2048
	v_pk_add_f32 v[92:93], v[92:93], v[94:95]
	s_nop 0
	v_add_f32_e32 v92, v92, v93
	ds_bpermute_b32 v93, v72, v92
	s_waitcnt lgkmcnt(0)
	v_add_f32_e32 v92, v92, v93
	ds_bpermute_b32 v93, v73, v92
	s_waitcnt lgkmcnt(0)
	v_add_f32_e32 v92, v92, v93
	ds_bpermute_b32 v93, v74, v92
	s_waitcnt lgkmcnt(0)
	v_add_f32_e32 v92, v92, v93
	ds_bpermute_b32 v93, v75, v92
	s_waitcnt lgkmcnt(0)
	v_add_f32_e32 v92, v92, v93
	ds_bpermute_b32 v93, v76, v92
	s_waitcnt lgkmcnt(0)
	v_add_f32_e32 v92, v92, v93
	ds_bpermute_b32 v93, v77, v92
	s_waitcnt lgkmcnt(0)
	v_add_f32_e32 v92, v92, v93
	v_fmamk_f32 v92, v92, 0x3a000000, v78
	v_mul_f32_e32 v93, 0x4f800000, v92
	v_cmp_gt_f32_e32 vcc, s26, v92
	s_nop 1
	v_cndmask_b32_e32 v92, v92, v93, vcc
	v_sqrt_f32_e32 v93, v92
	s_nop 0
	v_add_u32_e32 v94, -1, v93
	v_fma_f32 v95, -v94, v93, v92
	v_cmp_ge_f32_e64 s[0:1], 0, v95
	v_add_u32_e32 v95, 1, v93
	s_nop 0
	v_cndmask_b32_e64 v94, v93, v94, s[0:1]
	v_fma_f32 v93, -v95, v93, v92
	v_cmp_lt_f32_e64 s[0:1], 0, v93
	s_nop 1
	v_cndmask_b32_e64 v93, v94, v95, s[0:1]
	v_mul_f32_e32 v94, 0x37800000, v93
	v_cndmask_b32_e32 v93, v93, v94, vcc
	v_cmp_class_f32_e32 vcc, v92, v79
	s_nop 1
	v_cndmask_b32_e32 v92, v93, v92, vcc
	v_div_scale_f32 v93, s[0:1], v92, v92, 1.0
	v_rcp_f32_e32 v94, v93
	s_nop 0
	v_fma_f32 v95, -v93, v94, 1.0
	v_fmac_f32_e32 v94, v95, v94
	v_div_scale_f32 v95, vcc, 1.0, v92, 1.0
	v_mul_f32_e32 v100, v95, v94
	v_fma_f32 v101, -v93, v100, v95
	v_fmac_f32_e32 v100, v101, v94
	v_fma_f32 v93, -v93, v100, v95
	v_div_fmas_f32 v93, v93, v94, v100
	v_div_fixup_f32 v92, v93, v92, 1.0
	v_pk_mul_f32 v[70:71], v[92:93], v[70:71] op_sel_hi:[0,1]
	v_pk_mul_f32 v[68:69], v[92:93], v[68:69] op_sel_hi:[0,1]
	s_waitcnt vmcnt(8)
	v_pk_mul_f32 v[68:69], v[80:81], v[68:69]
	v_pk_mul_f32 v[70:71], v[82:83], v[70:71]
	s_waitcnt vmcnt(6)
	v_pk_add_f32 v[80:81], v[90:91], 1.0 op_sel_hi:[1,0]
	v_pk_add_f32 v[82:83], v[88:89], 1.0 op_sel_hi:[1,0]
	v_pk_fma_f32 v[70:71], v[80:81], v[70:71], v[86:87]
	v_pk_fma_f32 v[68:69], v[82:83], v[68:69], v[84:85]
	v_lshl_add_u64 v[88:89], s[12:13], 2, v[18:19]
	global_store_dwordx4 v[88:89], v[68:71], off
	s_nop 1
	v_add_co_u32_e32 v80, vcc, s5, v98
	s_nop 1
	v_addc_co_u32_e32 v81, vcc, 0, v99, vcc
	v_add_co_u32_e32 v68, vcc, s5, v96
	s_nop 1
	v_addc_co_u32_e32 v69, vcc, 0, v97, vcc
	v_add_co_u32_e32 v70, vcc, s5, v88
	s_nop 1
	v_addc_co_u32_e32 v71, vcc, 0, v89, vcc
	v_pk_mul_f32 v[64:65], v[92:93], v[64:65] op_sel_hi:[0,1]
	v_pk_mul_f32 v[66:67], v[92:93], v[66:67] op_sel_hi:[0,1]
	v_pk_mul_f32 v[60:61], v[92:93], v[60:61] op_sel_hi:[0,1]
	v_pk_mul_f32 v[62:63], v[92:93], v[62:63] op_sel_hi:[0,1]
	v_pk_mul_f32 v[56:57], v[92:93], v[56:57] op_sel_hi:[0,1]
	v_pk_mul_f32 v[58:59], v[92:93], v[58:59] op_sel_hi:[0,1]
	v_pk_mul_f32 v[52:53], v[92:93], v[52:53] op_sel_hi:[0,1]
	v_pk_mul_f32 v[54:55], v[92:93], v[54:55] op_sel_hi:[0,1]
	v_pk_mul_f32 v[48:49], v[92:93], v[48:49] op_sel_hi:[0,1]
	v_pk_mul_f32 v[50:51], v[92:93], v[50:51] op_sel_hi:[0,1]
	v_pk_mul_f32 v[44:45], v[92:93], v[44:45] op_sel_hi:[0,1]
	v_pk_mul_f32 v[46:47], v[92:93], v[46:47] op_sel_hi:[0,1]
	v_pk_mul_f32 v[42:43], v[92:93], v[42:43] op_sel_hi:[0,1]
	v_pk_mul_f32 v[40:41], v[92:93], v[40:41] op_sel_hi:[0,1]
	s_waitcnt vmcnt(6)
	v_pk_mul_f32 v[66:67], v[222:223], v[66:67]
	v_pk_mul_f32 v[64:65], v[220:221], v[64:65]
	s_waitcnt vmcnt(5)
	v_pk_add_f32 v[220:221], v[226:227], 1.0 op_sel_hi:[1,0]
	v_pk_add_f32 v[222:223], v[224:225], 1.0 op_sel_hi:[1,0]
	s_waitcnt vmcnt(4)
	v_pk_fma_f32 v[66:67], v[220:221], v[66:67], v[230:231]
	v_pk_fma_f32 v[64:65], v[222:223], v[64:65], v[228:229]
	global_store_dwordx4 v[88:89], v[64:67], off offset:1024
	global_load_dwordx4 v[220:223], v[4:5], off offset:3072
	global_load_dwordx4 v[224:227], v[98:99], off offset:3072
	global_load_dwordx4 v[228:231], v[96:97], off offset:3072
	s_waitcnt vmcnt(7)
	v_pk_mul_f32 v[62:63], v[234:235], v[62:63]
	v_pk_mul_f32 v[60:61], v[232:233], v[60:61]
	s_waitcnt vmcnt(6)
	v_pk_add_f32 v[232:233], v[238:239], 1.0 op_sel_hi:[1,0]
	v_pk_add_f32 v[234:235], v[236:237], 1.0 op_sel_hi:[1,0]
	s_waitcnt vmcnt(5)
	v_pk_fma_f32 v[62:63], v[232:233], v[62:63], v[242:243]
	v_pk_fma_f32 v[60:61], v[234:235], v[60:61], v[240:241]
	global_store_dwordx4 v[88:89], v[60:63], off offset:2048
	global_load_dwordx4 v[232:235], v[6:7], off
	global_load_dwordx4 v[236:239], v[80:81], off
	global_load_dwordx4 v[240:243], v[68:69], off
	s_waitcnt vmcnt(6)
	v_pk_mul_f32 v[58:59], v[222:223], v[58:59]
	v_pk_mul_f32 v[56:57], v[220:221], v[56:57]
	s_waitcnt vmcnt(5)
	v_pk_add_f32 v[220:221], v[226:227], 1.0 op_sel_hi:[1,0]
	v_pk_add_f32 v[222:223], v[224:225], 1.0 op_sel_hi:[1,0]
	s_waitcnt vmcnt(4)
	v_pk_fma_f32 v[56:57], v[222:223], v[56:57], v[228:229]
	v_pk_fma_f32 v[58:59], v[220:221], v[58:59], v[230:231]
	global_store_dwordx4 v[88:89], v[56:59], off offset:3072
	global_load_dwordx4 v[220:223], v[8:9], off
	global_load_dwordx4 v[224:227], v[80:81], off offset:1024
	global_load_dwordx4 v[228:231], v[68:69], off offset:1024
	s_waitcnt vmcnt(6)
	v_pk_mul_f32 v[54:55], v[234:235], v[54:55]
	v_pk_mul_f32 v[52:53], v[232:233], v[52:53]
	s_waitcnt vmcnt(5)
	v_pk_add_f32 v[232:233], v[238:239], 1.0 op_sel_hi:[1,0]
	v_pk_add_f32 v[234:235], v[236:237], 1.0 op_sel_hi:[1,0]
	s_waitcnt vmcnt(4)
	v_pk_fma_f32 v[52:53], v[234:235], v[52:53], v[240:241]
	v_pk_fma_f32 v[54:55], v[232:233], v[54:55], v[242:243]
	global_store_dwordx4 v[70:71], v[52:55], off
	global_load_dwordx4 v[232:235], v[10:11], off
	global_load_dwordx4 v[236:239], v[80:81], off offset:2048
	global_load_dwordx4 v[240:243], v[68:69], off offset:2048
	s_waitcnt vmcnt(6)
	v_pk_mul_f32 v[50:51], v[50:51], v[222:223]
	v_pk_mul_f32 v[48:49], v[48:49], v[220:221]
	s_waitcnt vmcnt(5)
	v_pk_add_f32 v[220:221], v[226:227], 1.0 op_sel_hi:[1,0]
	v_pk_add_f32 v[222:223], v[224:225], 1.0 op_sel_hi:[1,0]
	s_waitcnt vmcnt(4)
	v_pk_fma_f32 v[50:51], v[50:51], v[220:221], v[230:231]
	v_pk_fma_f32 v[48:49], v[48:49], v[222:223], v[228:229]
	global_store_dwordx4 v[70:71], v[48:51], off offset:1024
	global_load_dwordx4 v[220:223], v[12:13], off
	global_load_dwordx4 v[224:227], v[80:81], off offset:3072
	global_load_dwordx4 v[228:231], v[68:69], off offset:3072
	s_waitcnt vmcnt(6)
	v_pk_mul_f32 v[46:47], v[46:47], v[234:235]
	v_pk_mul_f32 v[44:45], v[44:45], v[232:233]
	s_waitcnt vmcnt(5)
	v_pk_add_f32 v[232:233], v[238:239], 1.0 op_sel_hi:[1,0]
	v_pk_add_f32 v[234:235], v[236:237], 1.0 op_sel_hi:[1,0]
	s_waitcnt vmcnt(4)
	v_pk_fma_f32 v[46:47], v[46:47], v[232:233], v[242:243]
	v_pk_fma_f32 v[44:45], v[44:45], v[234:235], v[240:241]
	global_store_dwordx4 v[70:71], v[44:47], off offset:2048
	s_waitcnt vmcnt(3)
	v_pk_mul_f32 v[222:223], v[40:41], v[222:223]
	v_pk_mul_f32 v[40:41], v[42:43], v[220:221]
	s_waitcnt vmcnt(2)
	v_pk_add_f32 v[42:43], v[226:227], 1.0 op_sel_hi:[1,0]
	v_pk_add_f32 v[220:221], v[224:225], 1.0 op_sel_hi:[1,0]
	s_waitcnt vmcnt(1)
	v_pk_fma_f32 v[42:43], v[222:223], v[42:43], v[230:231]
	v_pk_fma_f32 v[40:41], v[40:41], v[220:221], v[228:229]
	global_store_dwordx4 v[70:71], v[40:43], off offset:3072

.LBB0_874:
	v_pk_mul_f32 v[92:93], v[68:69], v[68:69]
	v_pk_mul_f32 v[94:95], v[64:65], v[64:65]
	v_pk_mul_f32 v[88:89], v[70:71], v[70:71]
	v_pk_mul_f32 v[90:91], v[66:67], v[66:67]
	v_mov_b32_e32 v96, v92
	v_mov_b32_e32 v97, v94
	v_mov_b32_e32 v94, v93
	v_pk_mul_f32 v[84:85], v[62:63], v[62:63]
	v_pk_mul_f32 v[86:87], v[60:61], v[60:61]
	v_pk_add_f32 v[92:93], v[96:97], v[94:95]
	v_mov_b32_e32 v94, v88
	v_mov_b32_e32 v95, v90
	v_mov_b32_e32 v90, v89
	v_pk_add_f32 v[88:89], v[94:95], v[90:91]
	v_pk_mov_b32 v[90:91], v[86:87], v[84:85] op_sel:[1,0]
	v_mov_b32_e32 v87, v85
	v_pk_add_f32 v[84:85], v[90:91], v[86:87]
	v_pk_add_f32 v[88:89], v[92:93], v[88:89]
	v_pk_add_f32 v[84:85], v[84:85], v[84:85] op_sel_hi:[0,1]
	v_mul_f32_e32 v84, v56, v56
	v_pk_fma_f32 v[86:87], v[56:57], v[56:57], v[84:85] op_sel_hi:[1,1,0]
	v_mul_f32_e32 v84, v58, v58
	v_pk_add_f32 v[88:89], v[88:89], v[88:89] op_sel_hi:[0,1]
	v_pk_fma_f32 v[90:91], v[58:59], v[58:59], v[84:85] op_sel_hi:[1,1,0]
	v_mul_f32_e32 v86, v54, v54
	v_mul_f32_e32 v90, v55, v55
	v_mul_f32_e32 v84, v52, v52
	v_mul_f32_e32 v88, v53, v53
	v_pk_mul_f32 v[80:81], v[50:51], v[50:51]
	v_pk_mul_f32 v[82:83], v[48:49], v[48:49]
	v_pk_add_f32 v[86:87], v[86:87], v[90:91]
	v_pk_add_f32 v[84:85], v[84:85], v[88:89]
	s_lshr_b32 s0, s2, 6
	v_pk_add_f32 v[84:85], v[86:87], v[84:85]
	v_pk_mov_b32 v[86:87], v[82:83], v[80:81] op_sel:[1,0]
	v_mov_b32_e32 v83, v81
	s_add_i32 s0, s0, 2
	s_ashr_i32 s1, s92, 14
	v_pk_add_f32 v[80:81], v[86:87], v[82:83]
	s_cmp_lt_i32 s92, 0x8000
	v_pk_add_f32 v[80:81], v[80:81], v[80:81] op_sel_hi:[0,1]
	s_cselect_b32 s0, s1, s0
	v_mul_f32_e32 v80, v44, v44
	v_pk_fma_f32 v[82:83], v[44:45], v[44:45], v[80:81] op_sel_hi:[1,1,0]
	v_mul_f32_e32 v80, v46, v46
	s_ashr_i32 s1, s0, 31
	v_pk_add_f32 v[84:85], v[84:85], v[84:85] op_sel_hi:[0,1]
	v_pk_fma_f32 v[86:87], v[46:47], v[46:47], v[80:81] op_sel_hi:[1,1,0]
	s_lshl_b64 s[0:1], s[0:1], 14
	v_mul_f32_e32 v82, v40, v40
	v_mul_f32_e32 v86, v41, v41
	v_mul_f32_e32 v80, v42, v42
	v_mul_f32_e32 v84, v43, v43
	v_lshl_add_u64 v[96:97], v[14:15], 0, s[0:1]
	v_pk_add_f32 v[92:93], v[82:83], v[86:87]
	v_pk_add_f32 v[94:95], v[80:81], v[84:85]
	global_load_dwordx4 v[80:83], v[4:5], off
	v_lshl_add_u64 v[98:99], v[16:17], 0, s[0:1]
	global_load_dwordx4 v[84:87], v[96:97], off
	global_load_dwordx4 v[88:91], v[98:99], off
	global_load_dwordx4 v[220:223], v[4:5], off offset:1024
	global_load_dwordx4 v[224:227], v[98:99], off offset:1024
	global_load_dwordx4 v[228:231], v[96:97], off offset:1024
	global_load_dwordx4 v[232:235], v[4:5], off offset:2048
	global_load_dwordx4 v[236:239], v[98:99], off offset:2048
	global_load_dwordx4 v[240:243], v[96:97], off offset:2048
	v_pk_add_f32 v[92:93], v[92:93], v[94:95]
	s_nop 0
	v_add_f32_e32 v92, v92, v93
	ds_bpermute_b32 v93, v72, v92
	s_waitcnt lgkmcnt(0)
	v_add_f32_e32 v92, v92, v93
	ds_bpermute_b32 v93, v73, v92
	s_waitcnt lgkmcnt(0)
	v_add_f32_e32 v92, v92, v93
	ds_bpermute_b32 v93, v74, v92
	s_waitcnt lgkmcnt(0)
	v_add_f32_e32 v92, v92, v93
	ds_bpermute_b32 v93, v75, v92
	s_waitcnt lgkmcnt(0)
	v_add_f32_e32 v92, v92, v93
	ds_bpermute_b32 v93, v76, v92
	s_waitcnt lgkmcnt(0)
	v_add_f32_e32 v92, v92, v93
	ds_bpermute_b32 v93, v77, v92
	s_waitcnt lgkmcnt(0)
	v_add_f32_e32 v92, v92, v93
	v_fmamk_f32 v92, v92, 0x3a000000, v78
	v_mul_f32_e32 v93, 0x4f800000, v92
	v_cmp_gt_f32_e32 vcc, s26, v92
	s_nop 1
	v_cndmask_b32_e32 v92, v92, v93, vcc
	v_sqrt_f32_e32 v93, v92
	s_nop 0
	v_add_u32_e32 v94, -1, v93
	v_fma_f32 v95, -v94, v93, v92
	v_cmp_ge_f32_e64 s[0:1], 0, v95
	v_add_u32_e32 v95, 1, v93
	s_nop 0
	v_cndmask_b32_e64 v94, v93, v94, s[0:1]
	v_fma_f32 v93, -v95, v93, v92
	v_cmp_lt_f32_e64 s[0:1], 0, v93
	s_nop 1
	v_cndmask_b32_e64 v93, v94, v95, s[0:1]
	v_mul_f32_e32 v94, 0x37800000, v93
	v_cndmask_b32_e32 v93, v93, v94, vcc
	v_cmp_class_f32_e32 vcc, v92, v79
	s_nop 1
	v_cndmask_b32_e32 v92, v93, v92, vcc
	v_div_scale_f32 v93, s[0:1], v92, v92, 1.0
	v_rcp_f32_e32 v94, v93
	s_nop 0
	v_fma_f32 v95, -v93, v94, 1.0
	v_fmac_f32_e32 v94, v95, v94
	v_div_scale_f32 v95, vcc, 1.0, v92, 1.0
	v_mul_f32_e32 v100, v95, v94
	v_fma_f32 v101, -v93, v100, v95
	v_fmac_f32_e32 v100, v101, v94
	v_fma_f32 v93, -v93, v100, v95
	v_div_fmas_f32 v93, v93, v94, v100
	v_div_fixup_f32 v92, v93, v92, 1.0
	v_pk_mul_f32 v[70:71], v[70:71], v[92:93] op_sel_hi:[1,0]
	v_pk_mul_f32 v[68:69], v[68:69], v[92:93] op_sel_hi:[1,0]
	s_waitcnt vmcnt(8)
	v_pk_mul_f32 v[70:71], v[82:83], v[70:71]
	v_pk_mul_f32 v[68:69], v[80:81], v[68:69]
	s_waitcnt vmcnt(6)
	v_pk_add_f32 v[80:81], v[90:91], 1.0 op_sel_hi:[1,0]
	v_pk_add_f32 v[82:83], v[88:89], 1.0 op_sel_hi:[1,0]
	v_pk_fma_f32 v[70:71], v[80:81], v[70:71], v[86:87]
	v_pk_fma_f32 v[68:69], v[82:83], v[68:69], v[84:85]
	global_store_dwordx4 v[20:21], v[68:71], off offset:-4096
	s_nop 1
	v_add_co_u32_e32 v80, vcc, s5, v98
	s_nop 1
	v_addc_co_u32_e32 v81, vcc, 0, v99, vcc
	v_add_co_u32_e32 v68, vcc, s5, v96
	s_nop 1
	v_addc_co_u32_e32 v69, vcc, 0, v97, vcc
	v_pk_mul_f32 v[64:65], v[64:65], v[92:93] op_sel_hi:[1,0]
	v_pk_mul_f32 v[66:67], v[66:67], v[92:93] op_sel_hi:[1,0]
	v_pk_mul_f32 v[60:61], v[60:61], v[92:93] op_sel_hi:[1,0]
	v_pk_mul_f32 v[62:63], v[62:63], v[92:93] op_sel_hi:[1,0]
	v_pk_mul_f32 v[56:57], v[56:57], v[92:93] op_sel_hi:[1,0]
	v_pk_mul_f32 v[58:59], v[58:59], v[92:93] op_sel_hi:[1,0]
	v_pk_mul_f32 v[54:55], v[54:55], v[92:93] op_sel_hi:[1,0]
	v_pk_mul_f32 v[52:53], v[52:53], v[92:93] op_sel_hi:[1,0]
	v_pk_mul_f32 v[48:49], v[48:49], v[92:93] op_sel_hi:[1,0]
	v_pk_mul_f32 v[50:51], v[50:51], v[92:93] op_sel_hi:[1,0]
	v_pk_mul_f32 v[44:45], v[44:45], v[92:93] op_sel_hi:[1,0]
	v_pk_mul_f32 v[46:47], v[46:47], v[92:93] op_sel_hi:[1,0]
	v_pk_mul_f32 v[40:41], v[40:41], v[92:93] op_sel_hi:[1,0]
	v_pk_mul_f32 v[42:43], v[42:43], v[92:93] op_sel_hi:[1,0]
	s_waitcnt vmcnt(6)
; #define NM_LOAD(SRCF, SRCB, RF, RB) do { if (SRCF) { _Pragma("unroll") for (int j = 0; j < 8; ++j) RF[j] = *(const f32x4*)(SRCF + 4 * lane + 256 * j); } \
;         else { _Pragma("unroll") for (int j = 0; j < 8; ++j) RB[j] = *(const v2u*)(SRCB + 4 * lane + 256 * j); } } while (0)
; template <bool F32OUT> __device__ __forceinline__ void norm_mod_rows(const float* fp, const float* fs, const bf16* bp, const bf16* bs, const float* g, const float* shift, const float* scale, int mstride, void* dst, int gw, int NGW, int lane, const float* part = nullptr, bf16* wb = nullptr) {
;     ...
;     for (int row0 = gw; row0 < MROWS; row0 += 2 * NGW) {
;         const int row1 = row0 + NGW; const bool has1 = row1 < MROWS;
;         f32x4 rf0[8], rf1[8]; v2u rb0[8], rb1[8];
;         NM_SRC(row0, sf0, sb0); NM_SRC(row1, sf1, sb1);
;         NM_LOAD(sf0, sb0, rf0, rb0);
;         if (has1) NM_LOAD(sf1, sb1, rf1, rb1);
;         NM_PROC(row0, sf0, rf0, rb0);
;         if (has1) NM_PROC(row1, sf1, rf1, rb1);
	v_pk_mul_f32 v[66:67], v[222:223], v[66:67]
	v_pk_mul_f32 v[64:65], v[220:221], v[64:65]
	s_waitcnt vmcnt(5)
	v_pk_add_f32 v[220:221], v[226:227], 1.0 op_sel_hi:[1,0]
	v_pk_add_f32 v[222:223], v[224:225], 1.0 op_sel_hi:[1,0]
	s_waitcnt vmcnt(4)
	v_pk_fma_f32 v[66:67], v[220:221], v[66:67], v[230:231]
	v_pk_fma_f32 v[64:65], v[222:223], v[64:65], v[228:229]
	global_store_dwordx4 v[20:21], v[64:67], off offset:-3072
	global_load_dwordx4 v[220:223], v[4:5], off offset:3072
	global_load_dwordx4 v[224:227], v[98:99], off offset:3072
	global_load_dwordx4 v[228:231], v[96:97], off offset:3072
	s_waitcnt vmcnt(7)
	v_pk_mul_f32 v[62:63], v[234:235], v[62:63]
	v_pk_mul_f32 v[60:61], v[232:233], v[60:61]
	s_waitcnt vmcnt(6)
	v_pk_add_f32 v[232:233], v[238:239], 1.0 op_sel_hi:[1,0]
	v_pk_add_f32 v[234:235], v[236:237], 1.0 op_sel_hi:[1,0]
	s_waitcnt vmcnt(5)
	v_pk_fma_f32 v[62:63], v[232:233], v[62:63], v[242:243]
	v_pk_fma_f32 v[60:61], v[234:235], v[60:61], v[240:241]
	global_store_dwordx4 v[20:21], v[60:63], off offset:-2048
	global_load_dwordx4 v[232:235], v[6:7], off
	global_load_dwordx4 v[236:239], v[80:81], off
	global_load_dwordx4 v[240:243], v[68:69], off
	s_waitcnt vmcnt(6)
	v_pk_mul_f32 v[58:59], v[222:223], v[58:59]
	v_pk_mul_f32 v[56:57], v[220:221], v[56:57]
	s_waitcnt vmcnt(5)
	v_pk_add_f32 v[220:221], v[226:227], 1.0 op_sel_hi:[1,0]
	v_pk_add_f32 v[222:223], v[224:225], 1.0 op_sel_hi:[1,0]
	s_waitcnt vmcnt(4)
	v_pk_fma_f32 v[56:57], v[222:223], v[56:57], v[228:229]
	v_pk_fma_f32 v[58:59], v[220:221], v[58:59], v[230:231]
	global_store_dwordx4 v[20:21], v[56:59], off offset:-1024
	global_load_dwordx4 v[220:223], v[8:9], off
	global_load_dwordx4 v[224:227], v[80:81], off offset:1024
	global_load_dwordx4 v[228:231], v[68:69], off offset:1024
	s_andn2_b64 vcc, exec, s[18:19]
	s_waitcnt vmcnt(6)
	v_pk_mul_f32 v[234:235], v[234:235], v[52:53]
	v_pk_mul_f32 v[52:53], v[232:233], v[54:55]
	s_waitcnt vmcnt(5)
	v_pk_add_f32 v[54:55], v[238:239], 1.0 op_sel_hi:[1,0]
	v_pk_add_f32 v[232:233], v[236:237], 1.0 op_sel_hi:[1,0]
	s_waitcnt vmcnt(4)
	v_pk_fma_f32 v[54:55], v[234:235], v[54:55], v[242:243]
	v_pk_fma_f32 v[52:53], v[52:53], v[232:233], v[240:241]
	global_store_dwordx4 v[20:21], v[52:55], off
	global_load_dwordx4 v[232:235], v[10:11], off
	global_load_dwordx4 v[236:239], v[80:81], off offset:2048
	global_load_dwordx4 v[240:243], v[68:69], off offset:2048
	s_waitcnt vmcnt(6)
	v_pk_mul_f32 v[50:51], v[50:51], v[222:223]
	v_pk_mul_f32 v[48:49], v[48:49], v[220:221]
	s_waitcnt vmcnt(5)
	v_pk_add_f32 v[220:221], v[226:227], 1.0 op_sel_hi:[1,0]
	v_pk_add_f32 v[222:223], v[224:225], 1.0 op_sel_hi:[1,0]
	s_waitcnt vmcnt(4)
	v_pk_fma_f32 v[50:51], v[50:51], v[220:221], v[230:231]
	v_pk_fma_f32 v[48:49], v[48:49], v[222:223], v[228:229]
	global_store_dwordx4 v[20:21], v[48:51], off offset:1024
	global_load_dwordx4 v[220:223], v[12:13], off
	global_load_dwordx4 v[224:227], v[80:81], off offset:3072
	global_load_dwordx4 v[228:231], v[68:69], off offset:3072
	s_waitcnt vmcnt(6)
	v_pk_mul_f32 v[46:47], v[46:47], v[234:235]
	v_pk_mul_f32 v[44:45], v[44:45], v[232:233]
	s_waitcnt vmcnt(5)
	v_pk_add_f32 v[232:233], v[238:239], 1.0 op_sel_hi:[1,0]
	v_pk_add_f32 v[234:235], v[236:237], 1.0 op_sel_hi:[1,0]
	s_waitcnt vmcnt(4)
	v_pk_fma_f32 v[46:47], v[46:47], v[232:233], v[242:243]
	v_pk_fma_f32 v[44:45], v[44:45], v[234:235], v[240:241]
	global_store_dwordx4 v[20:21], v[44:47], off offset:2048
	s_waitcnt vmcnt(3)
	v_pk_mul_f32 v[42:43], v[42:43], v[222:223]
	v_pk_mul_f32 v[40:41], v[40:41], v[220:221]
	s_waitcnt vmcnt(2)
	v_pk_add_f32 v[220:221], v[226:227], 1.0 op_sel_hi:[1,0]
	v_pk_add_f32 v[222:223], v[224:225], 1.0 op_sel_hi:[1,0]
	s_waitcnt vmcnt(1)
	v_pk_fma_f32 v[42:43], v[42:43], v[220:221], v[230:231]
	v_pk_fma_f32 v[40:41], v[40:41], v[222:223], v[228:229]
	global_store_dwordx4 v[20:21], v[40:43], off offset:3072
	s_cbranch_vccnz .LBB0_869
	s_add_i32 s2, s14, 0xffff8000
	v_lshlrev_b32_e32 v68, 16, v38
	v_and_b32_e32 v69, 0xffff0000, v38
	v_lshlrev_b32_e32 v70, 16, v39
	v_and_b32_e32 v71, 0xffff0000, v39
	v_lshlrev_b32_e32 v64, 16, v36
	v_and_b32_e32 v65, 0xffff0000, v36
	v_lshlrev_b32_e32 v66, 16, v37
	v_and_b32_e32 v67, 0xffff0000, v37
	v_lshlrev_b32_e32 v60, 16, v34
	v_and_b32_e32 v61, 0xffff0000, v34
	v_lshlrev_b32_e32 v62, 16, v35
	v_and_b32_e32 v63, 0xffff0000, v35
	v_lshlrev_b32_e32 v56, 16, v32
	v_and_b32_e32 v57, 0xffff0000, v32
	v_lshlrev_b32_e32 v58, 16, v33
	v_and_b32_e32 v59, 0xffff0000, v33
	v_lshlrev_b32_e32 v52, 16, v30
	v_and_b32_e32 v53, 0xffff0000, v30
	v_lshlrev_b32_e32 v54, 16, v31
	v_and_b32_e32 v55, 0xffff0000, v31
	v_lshlrev_b32_e32 v48, 16, v28
	v_and_b32_e32 v49, 0xffff0000, v28
	v_lshlrev_b32_e32 v50, 16, v29
	v_and_b32_e32 v51, 0xffff0000, v29
	v_lshlrev_b32_e32 v44, 16, v26
	v_and_b32_e32 v45, 0xffff0000, v26
	v_lshlrev_b32_e32 v46, 16, v27
	v_and_b32_e32 v47, 0xffff0000, v27
	v_lshlrev_b32_e32 v42, 16, v24
	v_and_b32_e32 v43, 0xffff0000, v24
	v_lshlrev_b32_e32 v40, 16, v25
	s_andn2_b64 vcc, exec, s[16:17]
	v_and_b32_e32 v41, 0xffff0000, v25
	s_cbranch_vccnz .LBB0_868
	s_lshl_b64 s[0:1], s[2:3], 13
	v_lshl_add_u64 v[180:181], v[2:3], 0, s[0:1]
	v_add_co_u32_e32 v112, vcc, s5, v180
	global_load_dwordx4 v[80:83], v[180:181], off
	global_load_dwordx4 v[84:87], v[180:181], off offset:1024
	global_load_dwordx4 v[88:91], v[180:181], off offset:2048
	global_load_dwordx4 v[92:95], v[180:181], off offset:3072
	v_addc_co_u32_e32 v113, vcc, 0, v181, vcc
	v_add_co_u32_e32 v140, vcc, s21, v180
	global_load_dwordx4 v[96:99], v[112:113], off
	global_load_dwordx4 v[100:103], v[112:113], off offset:1024
	global_load_dwordx4 v[104:107], v[112:113], off offset:2048
	global_load_dwordx4 v[108:111], v[112:113], off offset:3072
	v_addc_co_u32_e32 v141, vcc, 0, v181, vcc
	v_add_co_u32_e32 v124, vcc, s20, v180
	global_load_dwordx4 v[112:115], v[140:141], off offset:-4096
	s_nop 0
	v_addc_co_u32_e32 v125, vcc, 0, v181, vcc
	v_add_co_u32_e32 v172, vcc, s23, v180
	global_load_dwordx4 v[116:119], v[124:125], off offset:1024
	global_load_dwordx4 v[120:123], v[124:125], off offset:2048
	s_nop 0
	global_load_dwordx4 v[124:127], v[124:125], off offset:3072
	s_nop 0
	global_load_dwordx4 v[128:131], v[140:141], off
	global_load_dwordx4 v[132:135], v[140:141], off offset:1024
	global_load_dwordx4 v[136:139], v[140:141], off offset:2048
	s_nop 0
	global_load_dwordx4 v[140:143], v[140:141], off offset:3072
	v_addc_co_u32_e32 v173, vcc, 0, v181, vcc
	v_add_co_u32_e32 v156, vcc, s22, v180
	global_load_dwordx4 v[144:147], v[172:173], off offset:-4096
	s_nop 0
	v_addc_co_u32_e32 v157, vcc, 0, v181, vcc
	v_add_co_u32_e32 v204, vcc, s25, v180
	global_load_dwordx4 v[148:151], v[156:157], off offset:1024
	global_load_dwordx4 v[152:155], v[156:157], off offset:2048
	s_nop 0
	global_load_dwordx4 v[156:159], v[156:157], off offset:3072
	s_nop 0
	global_load_dwordx4 v[160:163], v[172:173], off
	global_load_dwordx4 v[164:167], v[172:173], off offset:1024
	global_load_dwordx4 v[168:171], v[172:173], off offset:2048
	v_addc_co_u32_e32 v205, vcc, 0, v181, vcc
	v_add_co_u32_e32 v188, vcc, s24, v180
	global_load_dwordx4 v[172:175], v[172:173], off offset:3072
	s_nop 0
	global_load_dwordx4 v[176:179], v[204:205], off offset:-4096
	v_addc_co_u32_e32 v189, vcc, 0, v181, vcc
	global_load_dwordx4 v[180:183], v[188:189], off offset:1024
	global_load_dwordx4 v[184:187], v[188:189], off offset:2048
	s_nop 0
	global_load_dwordx4 v[188:191], v[188:189], off offset:3072
	s_nop 0
	global_load_dwordx4 v[192:195], v[204:205], off
	global_load_dwordx4 v[196:199], v[204:205], off offset:1024
	global_load_dwordx4 v[200:203], v[204:205], off offset:2048
	s_nop 0
	global_load_dwordx4 v[204:207], v[204:205], off offset:3072
	s_waitcnt vmcnt(31)
	v_pk_add_f32 v[70:71], v[82:83], v[70:71]
	v_pk_add_f32 v[68:69], v[80:81], v[68:69]
	s_waitcnt vmcnt(30)
	v_pk_add_f32 v[66:67], v[86:87], v[66:67]
	v_pk_add_f32 v[64:65], v[84:85], v[64:65]
	s_waitcnt vmcnt(29)
	v_pk_add_f32 v[62:63], v[90:91], v[62:63]
	v_pk_add_f32 v[60:61], v[88:89], v[60:61]
	s_waitcnt vmcnt(28)
	v_pk_add_f32 v[58:59], v[94:95], v[58:59]
	v_pk_add_f32 v[56:57], v[92:93], v[56:57]
	s_waitcnt vmcnt(27)
	v_pk_add_f32 v[54:55], v[98:99], v[54:55]
	v_pk_add_f32 v[52:53], v[96:97], v[52:53]
	s_waitcnt vmcnt(26)
	v_pk_add_f32 v[50:51], v[102:103], v[50:51]
	v_pk_add_f32 v[48:49], v[100:101], v[48:49]
	s_waitcnt vmcnt(25)
	v_pk_add_f32 v[46:47], v[106:107], v[46:47]
	v_pk_add_f32 v[44:45], v[104:105], v[44:45]
	s_waitcnt vmcnt(24)
	v_pk_add_f32 v[40:41], v[110:111], v[40:41]
	v_pk_add_f32 v[42:43], v[108:109], v[42:43]
	s_waitcnt vmcnt(23)
	v_pk_add_f32 v[70:71], v[70:71], v[114:115]
	v_pk_add_f32 v[68:69], v[68:69], v[112:113]
	s_waitcnt vmcnt(22)
	v_pk_add_f32 v[66:67], v[66:67], v[118:119]
	v_pk_add_f32 v[64:65], v[64:65], v[116:117]
	s_waitcnt vmcnt(21)
	v_pk_add_f32 v[62:63], v[62:63], v[122:123]
	v_pk_add_f32 v[60:61], v[60:61], v[120:121]
	s_waitcnt vmcnt(20)
	v_pk_add_f32 v[58:59], v[58:59], v[126:127]
	v_pk_add_f32 v[56:57], v[56:57], v[124:125]
	s_waitcnt vmcnt(19)
	v_pk_add_f32 v[54:55], v[54:55], v[130:131]
	v_pk_add_f32 v[52:53], v[52:53], v[128:129]
	s_waitcnt vmcnt(18)
	v_pk_add_f32 v[50:51], v[50:51], v[134:135]
	v_pk_add_f32 v[48:49], v[48:49], v[132:133]
	s_waitcnt vmcnt(17)
	v_pk_add_f32 v[46:47], v[46:47], v[138:139]
	v_pk_add_f32 v[44:45], v[44:45], v[136:137]
	s_waitcnt vmcnt(16)
	v_pk_add_f32 v[40:41], v[40:41], v[142:143]
	v_pk_add_f32 v[42:43], v[42:43], v[140:141]
	s_waitcnt vmcnt(15)
	v_pk_add_f32 v[70:71], v[70:71], v[146:147]
	v_pk_add_f32 v[68:69], v[68:69], v[144:145]
	s_waitcnt vmcnt(14)
	v_pk_add_f32 v[66:67], v[66:67], v[150:151]
	v_pk_add_f32 v[64:65], v[64:65], v[148:149]
	s_waitcnt vmcnt(13)
	v_pk_add_f32 v[62:63], v[62:63], v[154:155]
	v_pk_add_f32 v[60:61], v[60:61], v[152:153]
	s_waitcnt vmcnt(12)
	v_pk_add_f32 v[58:59], v[58:59], v[158:159]
	v_pk_add_f32 v[56:57], v[56:57], v[156:157]
	s_waitcnt vmcnt(11)
	v_pk_add_f32 v[54:55], v[54:55], v[162:163]
	v_pk_add_f32 v[52:53], v[52:53], v[160:161]
	s_waitcnt vmcnt(10)
	v_pk_add_f32 v[50:51], v[50:51], v[166:167]
	v_pk_add_f32 v[48:49], v[48:49], v[164:165]
	s_waitcnt vmcnt(9)
	v_pk_add_f32 v[46:47], v[46:47], v[170:171]
	v_pk_add_f32 v[44:45], v[44:45], v[168:169]
	s_waitcnt vmcnt(8)
	v_pk_add_f32 v[40:41], v[40:41], v[174:175]
	v_pk_add_f32 v[42:43], v[42:43], v[172:173]
	s_waitcnt vmcnt(7)
	v_pk_add_f32 v[70:71], v[70:71], v[178:179]
	v_pk_add_f32 v[68:69], v[68:69], v[176:177]
	s_waitcnt vmcnt(6)
	v_pk_add_f32 v[66:67], v[66:67], v[182:183]
	v_pk_add_f32 v[64:65], v[64:65], v[180:181]
	s_waitcnt vmcnt(5)
	v_pk_add_f32 v[62:63], v[62:63], v[186:187]
	v_pk_add_f32 v[60:61], v[60:61], v[184:185]
	s_waitcnt vmcnt(4)
	v_pk_add_f32 v[58:59], v[58:59], v[190:191]
	v_pk_add_f32 v[56:57], v[56:57], v[188:189]
	s_waitcnt vmcnt(3)
	v_pk_add_f32 v[54:55], v[54:55], v[194:195]
	v_pk_add_f32 v[52:53], v[52:53], v[192:193]
	s_waitcnt vmcnt(2)
	v_pk_add_f32 v[50:51], v[50:51], v[198:199]
	v_pk_add_f32 v[48:49], v[48:49], v[196:197]
	s_waitcnt vmcnt(1)
	v_pk_add_f32 v[46:47], v[46:47], v[202:203]
	v_pk_add_f32 v[44:45], v[44:45], v[200:201]
	s_waitcnt vmcnt(0)
	v_pk_add_f32 v[40:41], v[40:41], v[206:207]
	v_pk_add_f32 v[42:43], v[42:43], v[204:205]
	s_branch .LBB0_868
